# adaLN silu table shared between the two virtual blocks of a workgroup: each stages half of it and writes both LDS halves
# baseline (speedup 1.0000x reference)
.LBB0_34:
	s_or_saveexec_b64 s[0:1], s[52:53]
	s_mov_b64 s[52:53], 0
	s_xor_b64 exec, exec, s[0:1]
	s_cbranch_execz .LBB0_42
	v_mov_b32_e32 v2, v80
	v_mov_b32_e32 v3, v7
	v_lshrrev_b32_e32 v4, 8, v132
	v_mov_b32_e32 v5, s66
	v_mov_b32_e32 v8, s72
	v_readfirstlane_b32 s54, v4
	v_mov_b32_e32 v4, s65
	ds_read_b64 v[252:253], v4
	ds_read_b64 v[254:255], v5
	ds_read_b64 v[194:195], v8
	v_lshlrev_b32_e32 v8, 2, v3
	v_lshlrev_b32_e32 v4, 2, v60
	s_waitcnt lgkmcnt(0)
	v_add_co_u32_e32 v252, vcc, v252, v8
	v_addc_co_u32_e32 v253, vcc, 0, v253, vcc
	v_add_co_u32_e32 v254, vcc, v254, v8
	v_addc_co_u32_e32 v255, vcc, 0, v255, vcc
	v_add_co_u32_e32 v194, vcc, v194, v10
	v_addc_co_u32_e32 v195, vcc, v195, v11, vcc
	v_add_co_u32_e32 v194, vcc, v194, v4
	v_addc_co_u32_e32 v195, vcc, 0, v195, vcc
	s_cmp_lg_u32 s54, 0
	s_cbranch_scc1 .Lsilu_hb1
	v_add_u32_e32 v251, 0x12000, v2
	global_load_dword v214, v[252:253], off
	global_load_dword v215, v[252:253], off offset:1024
	global_load_dword v216, v[252:253], off offset:2048
	global_load_dword v217, v[252:253], off offset:3072
	v_add_co_u32_e32 v252, vcc, 0x1000, v252
	v_addc_co_u32_e32 v253, vcc, 0, v253, vcc
	global_load_dword v218, v[252:253], off
	global_load_dword v219, v[252:253], off offset:1024
	global_load_dword v220, v[252:253], off offset:2048
	global_load_dword v221, v[252:253], off offset:3072
	v_add_co_u32_e32 v252, vcc, 0x1000, v252
	v_addc_co_u32_e32 v253, vcc, 0, v253, vcc
	global_load_dword v222, v[252:253], off
	global_load_dword v223, v[252:253], off offset:1024
	global_load_dword v224, v[252:253], off offset:2048
	global_load_dword v225, v[252:253], off offset:3072
	v_add_co_u32_e32 v252, vcc, 0x1000, v252
	v_addc_co_u32_e32 v253, vcc, 0, v253, vcc
	global_load_dword v226, v[252:253], off
	global_load_dword v227, v[252:253], off offset:1024
	global_load_dword v228, v[252:253], off offset:2048
	global_load_dword v229, v[252:253], off offset:3072
	v_add_co_u32_e32 v252, vcc, 0x1000, v252
	v_addc_co_u32_e32 v253, vcc, 0, v253, vcc
	global_load_dword v230, v[252:253], off
	global_load_dword v231, v[252:253], off offset:1024
	global_load_dword v150, v[194:195], off
	v_add_co_u32_e32 v194, vcc, 0x6000, v194
	v_addc_co_u32_e32 v195, vcc, 0, v195, vcc
	global_load_dword v151, v[194:195], off
	v_add_co_u32_e32 v194, vcc, 0x6000, v194
	v_addc_co_u32_e32 v195, vcc, 0, v195, vcc
	global_load_dword v152, v[194:195], off
	v_add_co_u32_e32 v194, vcc, 0x6000, v194
	v_addc_co_u32_e32 v195, vcc, 0, v195, vcc
	global_load_dword v153, v[194:195], off
	v_add_co_u32_e32 v194, vcc, 0x6000, v194
	v_addc_co_u32_e32 v195, vcc, 0, v195, vcc
	global_load_dword v154, v[194:195], off
	v_add_co_u32_e32 v194, vcc, 0x6000, v194
	v_addc_co_u32_e32 v195, vcc, 0, v195, vcc
	global_load_dword v155, v[194:195], off
	v_add_co_u32_e32 v194, vcc, 0x6000, v194
	v_addc_co_u32_e32 v195, vcc, 0, v195, vcc
	global_load_dword v156, v[194:195], off
	v_add_co_u32_e32 v194, vcc, 0x6000, v194
	v_addc_co_u32_e32 v195, vcc, 0, v195, vcc
	global_load_dword v157, v[194:195], off
	v_add_co_u32_e32 v194, vcc, 0x6000, v194
	v_addc_co_u32_e32 v195, vcc, 0, v195, vcc
	global_load_dword v158, v[194:195], off
	v_add_co_u32_e32 v194, vcc, 0x6000, v194
	v_addc_co_u32_e32 v195, vcc, 0, v195, vcc
	global_load_dword v159, v[194:195], off
	v_add_co_u32_e32 v194, vcc, 0x6000, v194
	v_addc_co_u32_e32 v195, vcc, 0, v195, vcc
	global_load_dword v160, v[194:195], off
	v_add_co_u32_e32 v194, vcc, 0x6000, v194
	v_addc_co_u32_e32 v195, vcc, 0, v195, vcc
	global_load_dword v161, v[194:195], off
	v_add_co_u32_e32 v194, vcc, 0x6000, v194
	v_addc_co_u32_e32 v195, vcc, 0, v195, vcc
	global_load_dword v162, v[194:195], off
	v_add_co_u32_e32 v194, vcc, 0x6000, v194
	v_addc_co_u32_e32 v195, vcc, 0, v195, vcc
	global_load_dword v163, v[194:195], off
	v_add_co_u32_e32 v194, vcc, 0x6000, v194
	v_addc_co_u32_e32 v195, vcc, 0, v195, vcc
	global_load_dword v164, v[194:195], off
	v_add_co_u32_e32 v194, vcc, 0x6000, v194
	v_addc_co_u32_e32 v195, vcc, 0, v195, vcc
	global_load_dword v165, v[194:195], off
	v_add_co_u32_e32 v194, vcc, 0x6000, v194
	v_addc_co_u32_e32 v195, vcc, 0, v195, vcc
	global_load_dword v166, v[194:195], off
	v_add_co_u32_e32 v194, vcc, 0x6000, v194
	v_addc_co_u32_e32 v195, vcc, 0, v195, vcc
	global_load_dword v167, v[194:195], off
	v_add_co_u32_e32 v194, vcc, 0x6000, v194
	v_addc_co_u32_e32 v195, vcc, 0, v195, vcc
	global_load_dword v168, v[194:195], off
	v_add_co_u32_e32 v194, vcc, 0x6000, v194
	v_addc_co_u32_e32 v195, vcc, 0, v195, vcc
	global_load_dword v169, v[194:195], off
	v_add_co_u32_e32 v194, vcc, 0x6000, v194
	v_addc_co_u32_e32 v195, vcc, 0, v195, vcc
	global_load_dword v170, v[194:195], off
	v_add_co_u32_e32 v194, vcc, 0x6000, v194
	v_addc_co_u32_e32 v195, vcc, 0, v195, vcc
	global_load_dword v171, v[194:195], off
	v_add_co_u32_e32 v194, vcc, 0x6000, v194
	v_addc_co_u32_e32 v195, vcc, 0, v195, vcc
	global_load_dword v172, v[194:195], off
	v_add_co_u32_e32 v194, vcc, 0x6000, v194
	v_addc_co_u32_e32 v195, vcc, 0, v195, vcc
	global_load_dword v173, v[194:195], off
	v_add_co_u32_e32 v194, vcc, 0x6000, v194
	v_addc_co_u32_e32 v195, vcc, 0, v195, vcc
	s_waitcnt vmcnt(41)
	v_mov_b32_e32 v4, v214
	v_mul_f32_e32 v5, 0xbfb8aa3b, v4
	v_fma_f32 v8, v4, s67, -v5
	v_rndne_f32_e32 v23, v5
	v_fmac_f32_e32 v8, 0xb2a5705f, v4
	v_sub_f32_e32 v5, v5, v23
	v_add_f32_e32 v5, v5, v8
	v_cvt_i32_f32_e32 v23, v23
	v_exp_f32_e32 v5, v5
	v_cmp_nlt_f32_e32 vcc, s68, v4
	v_ldexp_f32 v5, v5, v23
	s_nop 0
	v_cndmask_b32_e32 v5, 0, v5, vcc
	v_cmp_ngt_f32_e32 vcc, s69, v4
	s_nop 1
	v_cndmask_b32_e32 v5, v95, v5, vcc
	v_add_f32_e32 v5, 1.0, v5
	v_div_scale_f32 v8, s[54:55], v5, v5, v4
	v_rcp_f32_e32 v23, v8
	v_div_scale_f32 v61, vcc, v4, v5, v4
	v_fma_f32 v65, -v8, v23, 1.0
	v_fmac_f32_e32 v23, v65, v23
	v_mul_f32_e32 v65, v61, v23
	v_fma_f32 v66, -v8, v65, v61
	v_fmac_f32_e32 v65, v66, v23
	v_fma_f32 v8, -v8, v65, v61
	v_div_fmas_f32 v8, v8, v23, v65
	v_div_fixup_f32 v4, v8, v5, v4
	ds_write_b32 v2, v4
	ds_write_b32 v251, v4
	s_waitcnt vmcnt(40)
	v_mov_b32_e32 v4, v215
	v_mul_f32_e32 v5, 0xbfb8aa3b, v4
	v_fma_f32 v8, v4, s67, -v5
	v_rndne_f32_e32 v23, v5
	v_fmac_f32_e32 v8, 0xb2a5705f, v4
	v_sub_f32_e32 v5, v5, v23
	v_add_f32_e32 v5, v5, v8
	v_cvt_i32_f32_e32 v23, v23
	v_exp_f32_e32 v5, v5
	v_cmp_nlt_f32_e32 vcc, s68, v4
	v_ldexp_f32 v5, v5, v23
	s_nop 0
	v_cndmask_b32_e32 v5, 0, v5, vcc
	v_cmp_ngt_f32_e32 vcc, s69, v4
	s_nop 1
	v_cndmask_b32_e32 v5, v95, v5, vcc
	v_add_f32_e32 v5, 1.0, v5
	v_div_scale_f32 v8, s[54:55], v5, v5, v4
	v_rcp_f32_e32 v23, v8
	v_div_scale_f32 v61, vcc, v4, v5, v4
	v_fma_f32 v65, -v8, v23, 1.0
	v_fmac_f32_e32 v23, v65, v23
	v_mul_f32_e32 v65, v61, v23
	v_fma_f32 v66, -v8, v65, v61
	v_fmac_f32_e32 v65, v66, v23
	v_fma_f32 v8, -v8, v65, v61
	v_div_fmas_f32 v8, v8, v23, v65
	v_div_fixup_f32 v4, v8, v5, v4
	ds_write_b32 v2, v4 offset:1024
	ds_write_b32 v251, v4 offset:1024
	s_waitcnt vmcnt(39)
	v_mov_b32_e32 v4, v216
	v_mul_f32_e32 v5, 0xbfb8aa3b, v4
	v_fma_f32 v8, v4, s67, -v5
	v_rndne_f32_e32 v23, v5
	v_fmac_f32_e32 v8, 0xb2a5705f, v4
	v_sub_f32_e32 v5, v5, v23
	v_add_f32_e32 v5, v5, v8
	v_cvt_i32_f32_e32 v23, v23
	v_exp_f32_e32 v5, v5
	v_cmp_nlt_f32_e32 vcc, s68, v4
	v_ldexp_f32 v5, v5, v23
	s_nop 0
	v_cndmask_b32_e32 v5, 0, v5, vcc
	v_cmp_ngt_f32_e32 vcc, s69, v4
	s_nop 1
	v_cndmask_b32_e32 v5, v95, v5, vcc
	v_add_f32_e32 v5, 1.0, v5
	v_div_scale_f32 v8, s[54:55], v5, v5, v4
	v_rcp_f32_e32 v23, v8
	v_div_scale_f32 v61, vcc, v4, v5, v4
	v_fma_f32 v65, -v8, v23, 1.0
	v_fmac_f32_e32 v23, v65, v23
	v_mul_f32_e32 v65, v61, v23
	v_fma_f32 v66, -v8, v65, v61
	v_fmac_f32_e32 v65, v66, v23
	v_fma_f32 v8, -v8, v65, v61
	v_div_fmas_f32 v8, v8, v23, v65
	v_div_fixup_f32 v4, v8, v5, v4
	ds_write_b32 v2, v4 offset:2048
	ds_write_b32 v251, v4 offset:2048
	s_waitcnt vmcnt(38)
	v_mov_b32_e32 v4, v217
	v_mul_f32_e32 v5, 0xbfb8aa3b, v4
	v_fma_f32 v8, v4, s67, -v5
	v_rndne_f32_e32 v23, v5
	v_fmac_f32_e32 v8, 0xb2a5705f, v4
	v_sub_f32_e32 v5, v5, v23
	v_add_f32_e32 v5, v5, v8
	v_cvt_i32_f32_e32 v23, v23
	v_exp_f32_e32 v5, v5
	v_cmp_nlt_f32_e32 vcc, s68, v4
	v_ldexp_f32 v5, v5, v23
	s_nop 0
	v_cndmask_b32_e32 v5, 0, v5, vcc
	v_cmp_ngt_f32_e32 vcc, s69, v4
	s_nop 1
	v_cndmask_b32_e32 v5, v95, v5, vcc
	v_add_f32_e32 v5, 1.0, v5
	v_div_scale_f32 v8, s[54:55], v5, v5, v4
	v_rcp_f32_e32 v23, v8
	v_div_scale_f32 v61, vcc, v4, v5, v4
	v_fma_f32 v65, -v8, v23, 1.0
	v_fmac_f32_e32 v23, v65, v23
	v_mul_f32_e32 v65, v61, v23
	v_fma_f32 v66, -v8, v65, v61
	v_fmac_f32_e32 v65, v66, v23
	v_fma_f32 v8, -v8, v65, v61
	v_div_fmas_f32 v8, v8, v23, v65
	v_div_fixup_f32 v4, v8, v5, v4
	ds_write_b32 v2, v4 offset:3072
	ds_write_b32 v251, v4 offset:3072
	s_waitcnt vmcnt(37)
	v_mov_b32_e32 v4, v218
	v_mul_f32_e32 v5, 0xbfb8aa3b, v4
	v_fma_f32 v8, v4, s67, -v5
	v_rndne_f32_e32 v23, v5
	v_fmac_f32_e32 v8, 0xb2a5705f, v4
	v_sub_f32_e32 v5, v5, v23
	v_add_f32_e32 v5, v5, v8
	v_cvt_i32_f32_e32 v23, v23
	v_exp_f32_e32 v5, v5
	v_cmp_nlt_f32_e32 vcc, s68, v4
	v_ldexp_f32 v5, v5, v23
	s_nop 0
	v_cndmask_b32_e32 v5, 0, v5, vcc
	v_cmp_ngt_f32_e32 vcc, s69, v4
	s_nop 1
	v_cndmask_b32_e32 v5, v95, v5, vcc
	v_add_f32_e32 v5, 1.0, v5
	v_div_scale_f32 v8, s[54:55], v5, v5, v4
	v_rcp_f32_e32 v23, v8
	v_div_scale_f32 v61, vcc, v4, v5, v4
	v_fma_f32 v65, -v8, v23, 1.0
	v_fmac_f32_e32 v23, v65, v23
	v_mul_f32_e32 v65, v61, v23
	v_fma_f32 v66, -v8, v65, v61
	v_fmac_f32_e32 v65, v66, v23
	v_fma_f32 v8, -v8, v65, v61
	v_div_fmas_f32 v8, v8, v23, v65
	v_div_fixup_f32 v4, v8, v5, v4
	ds_write_b32 v2, v4 offset:4096
	ds_write_b32 v251, v4 offset:4096
	s_waitcnt vmcnt(36)
	v_mov_b32_e32 v4, v219
	v_mul_f32_e32 v5, 0xbfb8aa3b, v4
	v_fma_f32 v8, v4, s67, -v5
	v_rndne_f32_e32 v23, v5
	v_fmac_f32_e32 v8, 0xb2a5705f, v4
	v_sub_f32_e32 v5, v5, v23
	v_add_f32_e32 v5, v5, v8
	v_cvt_i32_f32_e32 v23, v23
	v_exp_f32_e32 v5, v5
	v_cmp_nlt_f32_e32 vcc, s68, v4
	v_ldexp_f32 v5, v5, v23
	s_nop 0
	v_cndmask_b32_e32 v5, 0, v5, vcc
	v_cmp_ngt_f32_e32 vcc, s69, v4
	s_nop 1
	v_cndmask_b32_e32 v5, v95, v5, vcc
	v_add_f32_e32 v5, 1.0, v5
	v_div_scale_f32 v8, s[54:55], v5, v5, v4
	v_rcp_f32_e32 v23, v8
	v_div_scale_f32 v61, vcc, v4, v5, v4
	v_fma_f32 v65, -v8, v23, 1.0
	v_fmac_f32_e32 v23, v65, v23
	v_mul_f32_e32 v65, v61, v23
	v_fma_f32 v66, -v8, v65, v61
	v_fmac_f32_e32 v65, v66, v23
	v_fma_f32 v8, -v8, v65, v61
	v_div_fmas_f32 v8, v8, v23, v65
	v_div_fixup_f32 v4, v8, v5, v4
	ds_write_b32 v2, v4 offset:5120
	ds_write_b32 v251, v4 offset:5120
	s_waitcnt vmcnt(35)
	v_mov_b32_e32 v4, v220
	v_mul_f32_e32 v5, 0xbfb8aa3b, v4
	v_fma_f32 v8, v4, s67, -v5
	v_rndne_f32_e32 v23, v5
	v_fmac_f32_e32 v8, 0xb2a5705f, v4
	v_sub_f32_e32 v5, v5, v23
	v_add_f32_e32 v5, v5, v8
	v_cvt_i32_f32_e32 v23, v23
	v_exp_f32_e32 v5, v5
	v_cmp_nlt_f32_e32 vcc, s68, v4
	v_ldexp_f32 v5, v5, v23
	s_nop 0
	v_cndmask_b32_e32 v5, 0, v5, vcc
	v_cmp_ngt_f32_e32 vcc, s69, v4
	s_nop 1
	v_cndmask_b32_e32 v5, v95, v5, vcc
	v_add_f32_e32 v5, 1.0, v5
	v_div_scale_f32 v8, s[54:55], v5, v5, v4
	v_rcp_f32_e32 v23, v8
	v_div_scale_f32 v61, vcc, v4, v5, v4
	v_fma_f32 v65, -v8, v23, 1.0
	v_fmac_f32_e32 v23, v65, v23
	v_mul_f32_e32 v65, v61, v23
	v_fma_f32 v66, -v8, v65, v61
	v_fmac_f32_e32 v65, v66, v23
	v_fma_f32 v8, -v8, v65, v61
	v_div_fmas_f32 v8, v8, v23, v65
	v_div_fixup_f32 v4, v8, v5, v4
	ds_write_b32 v2, v4 offset:6144
	ds_write_b32 v251, v4 offset:6144
	s_waitcnt vmcnt(34)
	v_mov_b32_e32 v4, v221
	v_mul_f32_e32 v5, 0xbfb8aa3b, v4
	v_fma_f32 v8, v4, s67, -v5
	v_rndne_f32_e32 v23, v5
	v_fmac_f32_e32 v8, 0xb2a5705f, v4
	v_sub_f32_e32 v5, v5, v23
	v_add_f32_e32 v5, v5, v8
	v_cvt_i32_f32_e32 v23, v23
	v_exp_f32_e32 v5, v5
	v_cmp_nlt_f32_e32 vcc, s68, v4
	v_ldexp_f32 v5, v5, v23
	s_nop 0
	v_cndmask_b32_e32 v5, 0, v5, vcc
	v_cmp_ngt_f32_e32 vcc, s69, v4
	s_nop 1
	v_cndmask_b32_e32 v5, v95, v5, vcc
	v_add_f32_e32 v5, 1.0, v5
	v_div_scale_f32 v8, s[54:55], v5, v5, v4
	v_rcp_f32_e32 v23, v8
	v_div_scale_f32 v61, vcc, v4, v5, v4
	v_fma_f32 v65, -v8, v23, 1.0
	v_fmac_f32_e32 v23, v65, v23
	v_mul_f32_e32 v65, v61, v23
	v_fma_f32 v66, -v8, v65, v61
	v_fmac_f32_e32 v65, v66, v23
	v_fma_f32 v8, -v8, v65, v61
	v_div_fmas_f32 v8, v8, v23, v65
	v_div_fixup_f32 v4, v8, v5, v4
	ds_write_b32 v2, v4 offset:7168
	ds_write_b32 v251, v4 offset:7168
	s_waitcnt vmcnt(33)
	v_mov_b32_e32 v4, v222
	v_mul_f32_e32 v5, 0xbfb8aa3b, v4
	v_fma_f32 v8, v4, s67, -v5
	v_rndne_f32_e32 v23, v5
	v_fmac_f32_e32 v8, 0xb2a5705f, v4
	v_sub_f32_e32 v5, v5, v23
	v_add_f32_e32 v5, v5, v8
	v_cvt_i32_f32_e32 v23, v23
	v_exp_f32_e32 v5, v5
	v_cmp_nlt_f32_e32 vcc, s68, v4
	v_ldexp_f32 v5, v5, v23
	s_nop 0
	v_cndmask_b32_e32 v5, 0, v5, vcc
	v_cmp_ngt_f32_e32 vcc, s69, v4
	s_nop 1
	v_cndmask_b32_e32 v5, v95, v5, vcc
	v_add_f32_e32 v5, 1.0, v5
	v_div_scale_f32 v8, s[54:55], v5, v5, v4
	v_rcp_f32_e32 v23, v8
	v_div_scale_f32 v61, vcc, v4, v5, v4
	v_fma_f32 v65, -v8, v23, 1.0
	v_fmac_f32_e32 v23, v65, v23
	v_mul_f32_e32 v65, v61, v23
	v_fma_f32 v66, -v8, v65, v61
	v_fmac_f32_e32 v65, v66, v23
	v_fma_f32 v8, -v8, v65, v61
	v_div_fmas_f32 v8, v8, v23, v65
	v_div_fixup_f32 v4, v8, v5, v4
	ds_write_b32 v2, v4 offset:8192
	ds_write_b32 v251, v4 offset:8192
	s_waitcnt vmcnt(32)
	v_mov_b32_e32 v4, v223
	v_mul_f32_e32 v5, 0xbfb8aa3b, v4
	v_fma_f32 v8, v4, s67, -v5
	v_rndne_f32_e32 v23, v5
	v_fmac_f32_e32 v8, 0xb2a5705f, v4
	v_sub_f32_e32 v5, v5, v23
	v_add_f32_e32 v5, v5, v8
	v_cvt_i32_f32_e32 v23, v23
	v_exp_f32_e32 v5, v5
	v_cmp_nlt_f32_e32 vcc, s68, v4
	v_ldexp_f32 v5, v5, v23
	s_nop 0
	v_cndmask_b32_e32 v5, 0, v5, vcc
	v_cmp_ngt_f32_e32 vcc, s69, v4
	s_nop 1
	v_cndmask_b32_e32 v5, v95, v5, vcc
	v_add_f32_e32 v5, 1.0, v5
	v_div_scale_f32 v8, s[54:55], v5, v5, v4
	v_rcp_f32_e32 v23, v8
	v_div_scale_f32 v61, vcc, v4, v5, v4
	v_fma_f32 v65, -v8, v23, 1.0
	v_fmac_f32_e32 v23, v65, v23
	v_mul_f32_e32 v65, v61, v23
	v_fma_f32 v66, -v8, v65, v61
	v_fmac_f32_e32 v65, v66, v23
	v_fma_f32 v8, -v8, v65, v61
	v_div_fmas_f32 v8, v8, v23, v65
	v_div_fixup_f32 v4, v8, v5, v4
	ds_write_b32 v2, v4 offset:9216
	ds_write_b32 v251, v4 offset:9216
	s_waitcnt vmcnt(31)
	v_mov_b32_e32 v4, v224
	v_mul_f32_e32 v5, 0xbfb8aa3b, v4
	v_fma_f32 v8, v4, s67, -v5
	v_rndne_f32_e32 v23, v5
	v_fmac_f32_e32 v8, 0xb2a5705f, v4
	v_sub_f32_e32 v5, v5, v23
	v_add_f32_e32 v5, v5, v8
	v_cvt_i32_f32_e32 v23, v23
	v_exp_f32_e32 v5, v5
	v_cmp_nlt_f32_e32 vcc, s68, v4
	v_ldexp_f32 v5, v5, v23
	s_nop 0
	v_cndmask_b32_e32 v5, 0, v5, vcc
	v_cmp_ngt_f32_e32 vcc, s69, v4
	s_nop 1
	v_cndmask_b32_e32 v5, v95, v5, vcc
	v_add_f32_e32 v5, 1.0, v5
	v_div_scale_f32 v8, s[54:55], v5, v5, v4
	v_rcp_f32_e32 v23, v8
	v_div_scale_f32 v61, vcc, v4, v5, v4
	v_fma_f32 v65, -v8, v23, 1.0
	v_fmac_f32_e32 v23, v65, v23
	v_mul_f32_e32 v65, v61, v23
	v_fma_f32 v66, -v8, v65, v61
	v_fmac_f32_e32 v65, v66, v23
	v_fma_f32 v8, -v8, v65, v61
	v_div_fmas_f32 v8, v8, v23, v65
	v_div_fixup_f32 v4, v8, v5, v4
	ds_write_b32 v2, v4 offset:10240
	ds_write_b32 v251, v4 offset:10240
	s_waitcnt vmcnt(30)
	v_mov_b32_e32 v4, v225
	v_mul_f32_e32 v5, 0xbfb8aa3b, v4
	v_fma_f32 v8, v4, s67, -v5
	v_rndne_f32_e32 v23, v5
	v_fmac_f32_e32 v8, 0xb2a5705f, v4
	v_sub_f32_e32 v5, v5, v23
	v_add_f32_e32 v5, v5, v8
	v_cvt_i32_f32_e32 v23, v23
	v_exp_f32_e32 v5, v5
	v_cmp_nlt_f32_e32 vcc, s68, v4
	v_ldexp_f32 v5, v5, v23
	s_nop 0
	v_cndmask_b32_e32 v5, 0, v5, vcc
	v_cmp_ngt_f32_e32 vcc, s69, v4
	s_nop 1
	v_cndmask_b32_e32 v5, v95, v5, vcc
	v_add_f32_e32 v5, 1.0, v5
	v_div_scale_f32 v8, s[54:55], v5, v5, v4
	v_rcp_f32_e32 v23, v8
	v_div_scale_f32 v61, vcc, v4, v5, v4
	v_fma_f32 v65, -v8, v23, 1.0
	v_fmac_f32_e32 v23, v65, v23
	v_mul_f32_e32 v65, v61, v23
	v_fma_f32 v66, -v8, v65, v61
	v_fmac_f32_e32 v65, v66, v23
	v_fma_f32 v8, -v8, v65, v61
	v_div_fmas_f32 v8, v8, v23, v65
	v_div_fixup_f32 v4, v8, v5, v4
	ds_write_b32 v2, v4 offset:11264
	ds_write_b32 v251, v4 offset:11264
	s_waitcnt vmcnt(29)
	v_mov_b32_e32 v4, v226
	v_mul_f32_e32 v5, 0xbfb8aa3b, v4
	v_fma_f32 v8, v4, s67, -v5
	v_rndne_f32_e32 v23, v5
	v_fmac_f32_e32 v8, 0xb2a5705f, v4
	v_sub_f32_e32 v5, v5, v23
	v_add_f32_e32 v5, v5, v8
	v_cvt_i32_f32_e32 v23, v23
	v_exp_f32_e32 v5, v5
	v_cmp_nlt_f32_e32 vcc, s68, v4
	v_ldexp_f32 v5, v5, v23
	s_nop 0
	v_cndmask_b32_e32 v5, 0, v5, vcc
	v_cmp_ngt_f32_e32 vcc, s69, v4
	s_nop 1
	v_cndmask_b32_e32 v5, v95, v5, vcc
	v_add_f32_e32 v5, 1.0, v5
	v_div_scale_f32 v8, s[54:55], v5, v5, v4
	v_rcp_f32_e32 v23, v8
	v_div_scale_f32 v61, vcc, v4, v5, v4
	v_fma_f32 v65, -v8, v23, 1.0
	v_fmac_f32_e32 v23, v65, v23
	v_mul_f32_e32 v65, v61, v23
	v_fma_f32 v66, -v8, v65, v61
	v_fmac_f32_e32 v65, v66, v23
	v_fma_f32 v8, -v8, v65, v61
	v_div_fmas_f32 v8, v8, v23, v65
	v_div_fixup_f32 v4, v8, v5, v4
	ds_write_b32 v2, v4 offset:12288
	ds_write_b32 v251, v4 offset:12288
	s_waitcnt vmcnt(28)
	v_mov_b32_e32 v4, v227
	v_mul_f32_e32 v5, 0xbfb8aa3b, v4
	v_fma_f32 v8, v4, s67, -v5
	v_rndne_f32_e32 v23, v5
	v_fmac_f32_e32 v8, 0xb2a5705f, v4
	v_sub_f32_e32 v5, v5, v23
	v_add_f32_e32 v5, v5, v8
	v_cvt_i32_f32_e32 v23, v23
	v_exp_f32_e32 v5, v5
	v_cmp_nlt_f32_e32 vcc, s68, v4
	v_ldexp_f32 v5, v5, v23
	s_nop 0
	v_cndmask_b32_e32 v5, 0, v5, vcc
	v_cmp_ngt_f32_e32 vcc, s69, v4
	s_nop 1
	v_cndmask_b32_e32 v5, v95, v5, vcc
	v_add_f32_e32 v5, 1.0, v5
	v_div_scale_f32 v8, s[54:55], v5, v5, v4
	v_rcp_f32_e32 v23, v8
	v_div_scale_f32 v61, vcc, v4, v5, v4
	v_fma_f32 v65, -v8, v23, 1.0
	v_fmac_f32_e32 v23, v65, v23
	v_mul_f32_e32 v65, v61, v23
	v_fma_f32 v66, -v8, v65, v61
	v_fmac_f32_e32 v65, v66, v23
	v_fma_f32 v8, -v8, v65, v61
	v_div_fmas_f32 v8, v8, v23, v65
	v_div_fixup_f32 v4, v8, v5, v4
	ds_write_b32 v2, v4 offset:13312
	ds_write_b32 v251, v4 offset:13312
	s_waitcnt vmcnt(27)
	v_mov_b32_e32 v4, v228
	v_mul_f32_e32 v5, 0xbfb8aa3b, v4
	v_fma_f32 v8, v4, s67, -v5
	v_rndne_f32_e32 v23, v5
	v_fmac_f32_e32 v8, 0xb2a5705f, v4
	v_sub_f32_e32 v5, v5, v23
	v_add_f32_e32 v5, v5, v8
	v_cvt_i32_f32_e32 v23, v23
	v_exp_f32_e32 v5, v5
	v_cmp_nlt_f32_e32 vcc, s68, v4
	v_ldexp_f32 v5, v5, v23
	s_nop 0
	v_cndmask_b32_e32 v5, 0, v5, vcc
	v_cmp_ngt_f32_e32 vcc, s69, v4
	s_nop 1
	v_cndmask_b32_e32 v5, v95, v5, vcc
	v_add_f32_e32 v5, 1.0, v5
	v_div_scale_f32 v8, s[54:55], v5, v5, v4
	v_rcp_f32_e32 v23, v8
	v_div_scale_f32 v61, vcc, v4, v5, v4
	v_fma_f32 v65, -v8, v23, 1.0
	v_fmac_f32_e32 v23, v65, v23
	v_mul_f32_e32 v65, v61, v23
	v_fma_f32 v66, -v8, v65, v61
	v_fmac_f32_e32 v65, v66, v23
	v_fma_f32 v8, -v8, v65, v61
	v_div_fmas_f32 v8, v8, v23, v65
	v_div_fixup_f32 v4, v8, v5, v4
	ds_write_b32 v2, v4 offset:14336
	ds_write_b32 v251, v4 offset:14336
	s_waitcnt vmcnt(26)
	v_mov_b32_e32 v4, v229
	v_mul_f32_e32 v5, 0xbfb8aa3b, v4
	v_fma_f32 v8, v4, s67, -v5
	v_rndne_f32_e32 v23, v5
	v_fmac_f32_e32 v8, 0xb2a5705f, v4
	v_sub_f32_e32 v5, v5, v23
	v_add_f32_e32 v5, v5, v8
	v_cvt_i32_f32_e32 v23, v23
	v_exp_f32_e32 v5, v5
	v_cmp_nlt_f32_e32 vcc, s68, v4
	v_ldexp_f32 v5, v5, v23
	s_nop 0
	v_cndmask_b32_e32 v5, 0, v5, vcc
	v_cmp_ngt_f32_e32 vcc, s69, v4
	s_nop 1
	v_cndmask_b32_e32 v5, v95, v5, vcc
	v_add_f32_e32 v5, 1.0, v5
	v_div_scale_f32 v8, s[54:55], v5, v5, v4
	v_rcp_f32_e32 v23, v8
	v_div_scale_f32 v61, vcc, v4, v5, v4
	v_fma_f32 v65, -v8, v23, 1.0
	v_fmac_f32_e32 v23, v65, v23
	v_mul_f32_e32 v65, v61, v23
	v_fma_f32 v66, -v8, v65, v61
	v_fmac_f32_e32 v65, v66, v23
	v_fma_f32 v8, -v8, v65, v61
	v_div_fmas_f32 v8, v8, v23, v65
	v_div_fixup_f32 v4, v8, v5, v4
	ds_write_b32 v2, v4 offset:15360
	ds_write_b32 v251, v4 offset:15360
	s_waitcnt vmcnt(25)
	v_mov_b32_e32 v4, v230
	v_mul_f32_e32 v5, 0xbfb8aa3b, v4
	v_fma_f32 v8, v4, s67, -v5
	v_rndne_f32_e32 v23, v5
	v_fmac_f32_e32 v8, 0xb2a5705f, v4
	v_sub_f32_e32 v5, v5, v23
	v_add_f32_e32 v5, v5, v8
	v_cvt_i32_f32_e32 v23, v23
	v_exp_f32_e32 v5, v5
	v_cmp_nlt_f32_e32 vcc, s68, v4
	v_ldexp_f32 v5, v5, v23
	s_nop 0
	v_cndmask_b32_e32 v5, 0, v5, vcc
	v_cmp_ngt_f32_e32 vcc, s69, v4
	s_nop 1
	v_cndmask_b32_e32 v5, v95, v5, vcc
	v_add_f32_e32 v5, 1.0, v5
	v_div_scale_f32 v8, s[54:55], v5, v5, v4
	v_rcp_f32_e32 v23, v8
	v_div_scale_f32 v61, vcc, v4, v5, v4
	v_fma_f32 v65, -v8, v23, 1.0
	v_fmac_f32_e32 v23, v65, v23
	v_mul_f32_e32 v65, v61, v23
	v_fma_f32 v66, -v8, v65, v61
	v_fmac_f32_e32 v65, v66, v23
	v_fma_f32 v8, -v8, v65, v61
	v_div_fmas_f32 v8, v8, v23, v65
	v_div_fixup_f32 v4, v8, v5, v4
	ds_write_b32 v2, v4 offset:16384
	ds_write_b32 v251, v4 offset:16384
	s_waitcnt vmcnt(24)
	v_mov_b32_e32 v4, v231
	v_mul_f32_e32 v5, 0xbfb8aa3b, v4
	v_fma_f32 v8, v4, s67, -v5
	v_rndne_f32_e32 v23, v5
	v_fmac_f32_e32 v8, 0xb2a5705f, v4
	v_sub_f32_e32 v5, v5, v23
	v_add_f32_e32 v5, v5, v8
	v_cvt_i32_f32_e32 v23, v23
	v_exp_f32_e32 v5, v5
	v_cmp_nlt_f32_e32 vcc, s68, v4
	v_ldexp_f32 v5, v5, v23
	s_nop 0
	v_cndmask_b32_e32 v5, 0, v5, vcc
	v_cmp_ngt_f32_e32 vcc, s69, v4
	s_nop 1
	v_cndmask_b32_e32 v5, v95, v5, vcc
	v_add_f32_e32 v5, 1.0, v5
	v_div_scale_f32 v8, s[54:55], v5, v5, v4
	v_rcp_f32_e32 v23, v8
	v_div_scale_f32 v61, vcc, v4, v5, v4
	v_fma_f32 v65, -v8, v23, 1.0
	v_fmac_f32_e32 v23, v65, v23
	v_mul_f32_e32 v65, v61, v23
	v_fma_f32 v66, -v8, v65, v61
	v_fmac_f32_e32 v65, v66, v23
	v_fma_f32 v8, -v8, v65, v61
	v_div_fmas_f32 v8, v8, v23, v65
	v_div_fixup_f32 v4, v8, v5, v4
	ds_write_b32 v2, v4 offset:17408
	ds_write_b32 v251, v4 offset:17408
	s_branch .Lsilu_done
.Lsilu_hb1:
	v_add_u32_e32 v251, 0xfffee000, v2
	v_add_co_u32_e32 v252, vcc, 0x4800, v252
	v_addc_co_u32_e32 v253, vcc, 0, v253, vcc
	global_load_dword v214, v[252:253], off
	global_load_dword v215, v[252:253], off offset:1024
	global_load_dword v216, v[252:253], off offset:2048
	global_load_dword v217, v[252:253], off offset:3072
	v_add_co_u32_e32 v252, vcc, 0x1000, v252
	v_addc_co_u32_e32 v253, vcc, 0, v253, vcc
	global_load_dword v218, v[252:253], off
	global_load_dword v219, v[252:253], off offset:1024
	global_load_dword v220, v[252:253], off offset:2048
	global_load_dword v221, v[252:253], off offset:3072
	v_add_co_u32_e32 v252, vcc, 0x1000, v252
	v_addc_co_u32_e32 v253, vcc, 0, v253, vcc
	global_load_dword v222, v[252:253], off
	global_load_dword v223, v[252:253], off offset:1024
	global_load_dword v224, v[252:253], off offset:2048
	global_load_dword v225, v[252:253], off offset:3072
	v_add_co_u32_e32 v252, vcc, 0x1000, v252
	v_addc_co_u32_e32 v253, vcc, 0, v253, vcc
	global_load_dword v226, v[252:253], off
	global_load_dword v227, v[252:253], off offset:1024
	global_load_dword v228, v[254:255], off
	global_load_dword v229, v[254:255], off offset:1024
	global_load_dword v230, v[254:255], off offset:2048
	global_load_dword v231, v[254:255], off offset:3072
	global_load_dword v150, v[194:195], off
	v_add_co_u32_e32 v194, vcc, 0x6000, v194
	v_addc_co_u32_e32 v195, vcc, 0, v195, vcc
	global_load_dword v151, v[194:195], off
	v_add_co_u32_e32 v194, vcc, 0x6000, v194
	v_addc_co_u32_e32 v195, vcc, 0, v195, vcc
	global_load_dword v152, v[194:195], off
	v_add_co_u32_e32 v194, vcc, 0x6000, v194
	v_addc_co_u32_e32 v195, vcc, 0, v195, vcc
	global_load_dword v153, v[194:195], off
	v_add_co_u32_e32 v194, vcc, 0x6000, v194
	v_addc_co_u32_e32 v195, vcc, 0, v195, vcc
	global_load_dword v154, v[194:195], off
	v_add_co_u32_e32 v194, vcc, 0x6000, v194
	v_addc_co_u32_e32 v195, vcc, 0, v195, vcc
	global_load_dword v155, v[194:195], off
	v_add_co_u32_e32 v194, vcc, 0x6000, v194
	v_addc_co_u32_e32 v195, vcc, 0, v195, vcc
	global_load_dword v156, v[194:195], off
	v_add_co_u32_e32 v194, vcc, 0x6000, v194
	v_addc_co_u32_e32 v195, vcc, 0, v195, vcc
	global_load_dword v157, v[194:195], off
	v_add_co_u32_e32 v194, vcc, 0x6000, v194
	v_addc_co_u32_e32 v195, vcc, 0, v195, vcc
	global_load_dword v158, v[194:195], off
	v_add_co_u32_e32 v194, vcc, 0x6000, v194
	v_addc_co_u32_e32 v195, vcc, 0, v195, vcc
	global_load_dword v159, v[194:195], off
	v_add_co_u32_e32 v194, vcc, 0x6000, v194
	v_addc_co_u32_e32 v195, vcc, 0, v195, vcc
	global_load_dword v160, v[194:195], off
	v_add_co_u32_e32 v194, vcc, 0x6000, v194
	v_addc_co_u32_e32 v195, vcc, 0, v195, vcc
	global_load_dword v161, v[194:195], off
	v_add_co_u32_e32 v194, vcc, 0x6000, v194
	v_addc_co_u32_e32 v195, vcc, 0, v195, vcc
	global_load_dword v162, v[194:195], off
	v_add_co_u32_e32 v194, vcc, 0x6000, v194
	v_addc_co_u32_e32 v195, vcc, 0, v195, vcc
	global_load_dword v163, v[194:195], off
	v_add_co_u32_e32 v194, vcc, 0x6000, v194
	v_addc_co_u32_e32 v195, vcc, 0, v195, vcc
	global_load_dword v164, v[194:195], off
	v_add_co_u32_e32 v194, vcc, 0x6000, v194
	v_addc_co_u32_e32 v195, vcc, 0, v195, vcc
	global_load_dword v165, v[194:195], off
	v_add_co_u32_e32 v194, vcc, 0x6000, v194
	v_addc_co_u32_e32 v195, vcc, 0, v195, vcc
	global_load_dword v166, v[194:195], off
	v_add_co_u32_e32 v194, vcc, 0x6000, v194
	v_addc_co_u32_e32 v195, vcc, 0, v195, vcc
	global_load_dword v167, v[194:195], off
	v_add_co_u32_e32 v194, vcc, 0x6000, v194
	v_addc_co_u32_e32 v195, vcc, 0, v195, vcc
	global_load_dword v168, v[194:195], off
	v_add_co_u32_e32 v194, vcc, 0x6000, v194
	v_addc_co_u32_e32 v195, vcc, 0, v195, vcc
	global_load_dword v169, v[194:195], off
	v_add_co_u32_e32 v194, vcc, 0x6000, v194
	v_addc_co_u32_e32 v195, vcc, 0, v195, vcc
	global_load_dword v170, v[194:195], off
	v_add_co_u32_e32 v194, vcc, 0x6000, v194
	v_addc_co_u32_e32 v195, vcc, 0, v195, vcc
	global_load_dword v171, v[194:195], off
	v_add_co_u32_e32 v194, vcc, 0x6000, v194
	v_addc_co_u32_e32 v195, vcc, 0, v195, vcc
	global_load_dword v172, v[194:195], off
	v_add_co_u32_e32 v194, vcc, 0x6000, v194
	v_addc_co_u32_e32 v195, vcc, 0, v195, vcc
	global_load_dword v173, v[194:195], off
	v_add_co_u32_e32 v194, vcc, 0x6000, v194
	v_addc_co_u32_e32 v195, vcc, 0, v195, vcc
	s_waitcnt vmcnt(41)
	v_mov_b32_e32 v4, v214
	v_mul_f32_e32 v5, 0xbfb8aa3b, v4
	v_fma_f32 v8, v4, s67, -v5
	v_rndne_f32_e32 v23, v5
	v_fmac_f32_e32 v8, 0xb2a5705f, v4
	v_sub_f32_e32 v5, v5, v23
	v_add_f32_e32 v5, v5, v8
	v_cvt_i32_f32_e32 v23, v23
	v_exp_f32_e32 v5, v5
	v_cmp_nlt_f32_e32 vcc, s68, v4
	v_ldexp_f32 v5, v5, v23
	s_nop 0
	v_cndmask_b32_e32 v5, 0, v5, vcc
	v_cmp_ngt_f32_e32 vcc, s69, v4
	s_nop 1
	v_cndmask_b32_e32 v5, v95, v5, vcc
	v_add_f32_e32 v5, 1.0, v5
	v_div_scale_f32 v8, s[54:55], v5, v5, v4
	v_rcp_f32_e32 v23, v8
	v_div_scale_f32 v61, vcc, v4, v5, v4
	v_fma_f32 v65, -v8, v23, 1.0
	v_fmac_f32_e32 v23, v65, v23
	v_mul_f32_e32 v65, v61, v23
	v_fma_f32 v66, -v8, v65, v61
	v_fmac_f32_e32 v65, v66, v23
	v_fma_f32 v8, -v8, v65, v61
	v_div_fmas_f32 v8, v8, v23, v65
	v_div_fixup_f32 v4, v8, v5, v4
	ds_write_b32 v2, v4 offset:18432
	ds_write_b32 v251, v4 offset:18432
	s_waitcnt vmcnt(40)
	v_mov_b32_e32 v4, v215
	v_mul_f32_e32 v5, 0xbfb8aa3b, v4
	v_fma_f32 v8, v4, s67, -v5
	v_rndne_f32_e32 v23, v5
	v_fmac_f32_e32 v8, 0xb2a5705f, v4
	v_sub_f32_e32 v5, v5, v23
	v_add_f32_e32 v5, v5, v8
	v_cvt_i32_f32_e32 v23, v23
	v_exp_f32_e32 v5, v5
	v_cmp_nlt_f32_e32 vcc, s68, v4
	v_ldexp_f32 v5, v5, v23
	s_nop 0
	v_cndmask_b32_e32 v5, 0, v5, vcc
	v_cmp_ngt_f32_e32 vcc, s69, v4
	s_nop 1
	v_cndmask_b32_e32 v5, v95, v5, vcc
	v_add_f32_e32 v5, 1.0, v5
	v_div_scale_f32 v8, s[54:55], v5, v5, v4
	v_rcp_f32_e32 v23, v8
	v_div_scale_f32 v61, vcc, v4, v5, v4
	v_fma_f32 v65, -v8, v23, 1.0
	v_fmac_f32_e32 v23, v65, v23
	v_mul_f32_e32 v65, v61, v23
	v_fma_f32 v66, -v8, v65, v61
	v_fmac_f32_e32 v65, v66, v23
	v_fma_f32 v8, -v8, v65, v61
	v_div_fmas_f32 v8, v8, v23, v65
	v_div_fixup_f32 v4, v8, v5, v4
	ds_write_b32 v2, v4 offset:19456
	ds_write_b32 v251, v4 offset:19456
	s_waitcnt vmcnt(39)
	v_mov_b32_e32 v4, v216
	v_mul_f32_e32 v5, 0xbfb8aa3b, v4
	v_fma_f32 v8, v4, s67, -v5
	v_rndne_f32_e32 v23, v5
	v_fmac_f32_e32 v8, 0xb2a5705f, v4
	v_sub_f32_e32 v5, v5, v23
	v_add_f32_e32 v5, v5, v8
	v_cvt_i32_f32_e32 v23, v23
	v_exp_f32_e32 v5, v5
	v_cmp_nlt_f32_e32 vcc, s68, v4
	v_ldexp_f32 v5, v5, v23
	s_nop 0
	v_cndmask_b32_e32 v5, 0, v5, vcc
	v_cmp_ngt_f32_e32 vcc, s69, v4
	s_nop 1
	v_cndmask_b32_e32 v5, v95, v5, vcc
	v_add_f32_e32 v5, 1.0, v5
	v_div_scale_f32 v8, s[54:55], v5, v5, v4
	v_rcp_f32_e32 v23, v8
	v_div_scale_f32 v61, vcc, v4, v5, v4
	v_fma_f32 v65, -v8, v23, 1.0
	v_fmac_f32_e32 v23, v65, v23
	v_mul_f32_e32 v65, v61, v23
	v_fma_f32 v66, -v8, v65, v61
	v_fmac_f32_e32 v65, v66, v23
	v_fma_f32 v8, -v8, v65, v61
	v_div_fmas_f32 v8, v8, v23, v65
	v_div_fixup_f32 v4, v8, v5, v4
	ds_write_b32 v2, v4 offset:20480
	ds_write_b32 v251, v4 offset:20480
	s_waitcnt vmcnt(38)
	v_mov_b32_e32 v4, v217
	v_mul_f32_e32 v5, 0xbfb8aa3b, v4
	v_fma_f32 v8, v4, s67, -v5
	v_rndne_f32_e32 v23, v5
	v_fmac_f32_e32 v8, 0xb2a5705f, v4
	v_sub_f32_e32 v5, v5, v23
	v_add_f32_e32 v5, v5, v8
	v_cvt_i32_f32_e32 v23, v23
	v_exp_f32_e32 v5, v5
	v_cmp_nlt_f32_e32 vcc, s68, v4
	v_ldexp_f32 v5, v5, v23
	s_nop 0
	v_cndmask_b32_e32 v5, 0, v5, vcc
	v_cmp_ngt_f32_e32 vcc, s69, v4
	s_nop 1
	v_cndmask_b32_e32 v5, v95, v5, vcc
	v_add_f32_e32 v5, 1.0, v5
	v_div_scale_f32 v8, s[54:55], v5, v5, v4
	v_rcp_f32_e32 v23, v8
	v_div_scale_f32 v61, vcc, v4, v5, v4
	v_fma_f32 v65, -v8, v23, 1.0
	v_fmac_f32_e32 v23, v65, v23
	v_mul_f32_e32 v65, v61, v23
	v_fma_f32 v66, -v8, v65, v61
	v_fmac_f32_e32 v65, v66, v23
	v_fma_f32 v8, -v8, v65, v61
	v_div_fmas_f32 v8, v8, v23, v65
	v_div_fixup_f32 v4, v8, v5, v4
	ds_write_b32 v2, v4 offset:21504
	ds_write_b32 v251, v4 offset:21504
	s_waitcnt vmcnt(37)
	v_mov_b32_e32 v4, v218
	v_mul_f32_e32 v5, 0xbfb8aa3b, v4
	v_fma_f32 v8, v4, s67, -v5
	v_rndne_f32_e32 v23, v5
	v_fmac_f32_e32 v8, 0xb2a5705f, v4
	v_sub_f32_e32 v5, v5, v23
	v_add_f32_e32 v5, v5, v8
	v_cvt_i32_f32_e32 v23, v23
	v_exp_f32_e32 v5, v5
	v_cmp_nlt_f32_e32 vcc, s68, v4
	v_ldexp_f32 v5, v5, v23
	s_nop 0
	v_cndmask_b32_e32 v5, 0, v5, vcc
	v_cmp_ngt_f32_e32 vcc, s69, v4
	s_nop 1
	v_cndmask_b32_e32 v5, v95, v5, vcc
	v_add_f32_e32 v5, 1.0, v5
	v_div_scale_f32 v8, s[54:55], v5, v5, v4
	v_rcp_f32_e32 v23, v8
	v_div_scale_f32 v61, vcc, v4, v5, v4
	v_fma_f32 v65, -v8, v23, 1.0
	v_fmac_f32_e32 v23, v65, v23
	v_mul_f32_e32 v65, v61, v23
	v_fma_f32 v66, -v8, v65, v61
	v_fmac_f32_e32 v65, v66, v23
	v_fma_f32 v8, -v8, v65, v61
	v_div_fmas_f32 v8, v8, v23, v65
	v_div_fixup_f32 v4, v8, v5, v4
	ds_write_b32 v2, v4 offset:22528
	ds_write_b32 v251, v4 offset:22528
	s_waitcnt vmcnt(36)
	v_mov_b32_e32 v4, v219
	v_mul_f32_e32 v5, 0xbfb8aa3b, v4
	v_fma_f32 v8, v4, s67, -v5
	v_rndne_f32_e32 v23, v5
	v_fmac_f32_e32 v8, 0xb2a5705f, v4
	v_sub_f32_e32 v5, v5, v23
	v_add_f32_e32 v5, v5, v8
	v_cvt_i32_f32_e32 v23, v23
	v_exp_f32_e32 v5, v5
	v_cmp_nlt_f32_e32 vcc, s68, v4
	v_ldexp_f32 v5, v5, v23
	s_nop 0
	v_cndmask_b32_e32 v5, 0, v5, vcc
	v_cmp_ngt_f32_e32 vcc, s69, v4
	s_nop 1
	v_cndmask_b32_e32 v5, v95, v5, vcc
	v_add_f32_e32 v5, 1.0, v5
	v_div_scale_f32 v8, s[54:55], v5, v5, v4
	v_rcp_f32_e32 v23, v8
	v_div_scale_f32 v61, vcc, v4, v5, v4
	v_fma_f32 v65, -v8, v23, 1.0
	v_fmac_f32_e32 v23, v65, v23
	v_mul_f32_e32 v65, v61, v23
	v_fma_f32 v66, -v8, v65, v61
	v_fmac_f32_e32 v65, v66, v23
	v_fma_f32 v8, -v8, v65, v61
	v_div_fmas_f32 v8, v8, v23, v65
	v_div_fixup_f32 v4, v8, v5, v4
	ds_write_b32 v2, v4 offset:23552
	ds_write_b32 v251, v4 offset:23552
	s_waitcnt vmcnt(35)
	v_mov_b32_e32 v4, v220
	v_mul_f32_e32 v5, 0xbfb8aa3b, v4
	v_fma_f32 v8, v4, s67, -v5
	v_rndne_f32_e32 v23, v5
	v_fmac_f32_e32 v8, 0xb2a5705f, v4
	v_sub_f32_e32 v5, v5, v23
	v_add_f32_e32 v5, v5, v8
	v_cvt_i32_f32_e32 v23, v23
	v_exp_f32_e32 v5, v5
	v_cmp_nlt_f32_e32 vcc, s68, v4
	v_ldexp_f32 v5, v5, v23
	s_nop 0
	v_cndmask_b32_e32 v5, 0, v5, vcc
	v_cmp_ngt_f32_e32 vcc, s69, v4
	s_nop 1
	v_cndmask_b32_e32 v5, v95, v5, vcc
	v_add_f32_e32 v5, 1.0, v5
	v_div_scale_f32 v8, s[54:55], v5, v5, v4
	v_rcp_f32_e32 v23, v8
	v_div_scale_f32 v61, vcc, v4, v5, v4
	v_fma_f32 v65, -v8, v23, 1.0
	v_fmac_f32_e32 v23, v65, v23
	v_mul_f32_e32 v65, v61, v23
	v_fma_f32 v66, -v8, v65, v61
	v_fmac_f32_e32 v65, v66, v23
	v_fma_f32 v8, -v8, v65, v61
	v_div_fmas_f32 v8, v8, v23, v65
	v_div_fixup_f32 v4, v8, v5, v4
	ds_write_b32 v2, v4 offset:24576
	ds_write_b32 v251, v4 offset:24576
	s_waitcnt vmcnt(34)
	v_mov_b32_e32 v4, v221
	v_mul_f32_e32 v5, 0xbfb8aa3b, v4
	v_fma_f32 v8, v4, s67, -v5
	v_rndne_f32_e32 v23, v5
	v_fmac_f32_e32 v8, 0xb2a5705f, v4
	v_sub_f32_e32 v5, v5, v23
	v_add_f32_e32 v5, v5, v8
	v_cvt_i32_f32_e32 v23, v23
	v_exp_f32_e32 v5, v5
	v_cmp_nlt_f32_e32 vcc, s68, v4
	v_ldexp_f32 v5, v5, v23
	s_nop 0
	v_cndmask_b32_e32 v5, 0, v5, vcc
	v_cmp_ngt_f32_e32 vcc, s69, v4
	s_nop 1
	v_cndmask_b32_e32 v5, v95, v5, vcc
	v_add_f32_e32 v5, 1.0, v5
	v_div_scale_f32 v8, s[54:55], v5, v5, v4
	v_rcp_f32_e32 v23, v8
	v_div_scale_f32 v61, vcc, v4, v5, v4
	v_fma_f32 v65, -v8, v23, 1.0
	v_fmac_f32_e32 v23, v65, v23
	v_mul_f32_e32 v65, v61, v23
	v_fma_f32 v66, -v8, v65, v61
	v_fmac_f32_e32 v65, v66, v23
	v_fma_f32 v8, -v8, v65, v61
	v_div_fmas_f32 v8, v8, v23, v65
	v_div_fixup_f32 v4, v8, v5, v4
	ds_write_b32 v2, v4 offset:25600
	ds_write_b32 v251, v4 offset:25600
	s_waitcnt vmcnt(33)
	v_mov_b32_e32 v4, v222
	v_mul_f32_e32 v5, 0xbfb8aa3b, v4
	v_fma_f32 v8, v4, s67, -v5
	v_rndne_f32_e32 v23, v5
	v_fmac_f32_e32 v8, 0xb2a5705f, v4
	v_sub_f32_e32 v5, v5, v23
	v_add_f32_e32 v5, v5, v8
	v_cvt_i32_f32_e32 v23, v23
	v_exp_f32_e32 v5, v5
	v_cmp_nlt_f32_e32 vcc, s68, v4
	v_ldexp_f32 v5, v5, v23
	s_nop 0
	v_cndmask_b32_e32 v5, 0, v5, vcc
	v_cmp_ngt_f32_e32 vcc, s69, v4
	s_nop 1
	v_cndmask_b32_e32 v5, v95, v5, vcc
	v_add_f32_e32 v5, 1.0, v5
	v_div_scale_f32 v8, s[54:55], v5, v5, v4
	v_rcp_f32_e32 v23, v8
	v_div_scale_f32 v61, vcc, v4, v5, v4
	v_fma_f32 v65, -v8, v23, 1.0
	v_fmac_f32_e32 v23, v65, v23
	v_mul_f32_e32 v65, v61, v23
	v_fma_f32 v66, -v8, v65, v61
	v_fmac_f32_e32 v65, v66, v23
	v_fma_f32 v8, -v8, v65, v61
	v_div_fmas_f32 v8, v8, v23, v65
	v_div_fixup_f32 v4, v8, v5, v4
	ds_write_b32 v2, v4 offset:26624
	ds_write_b32 v251, v4 offset:26624
	s_waitcnt vmcnt(32)
	v_mov_b32_e32 v4, v223
	v_mul_f32_e32 v5, 0xbfb8aa3b, v4
	v_fma_f32 v8, v4, s67, -v5
	v_rndne_f32_e32 v23, v5
	v_fmac_f32_e32 v8, 0xb2a5705f, v4
	v_sub_f32_e32 v5, v5, v23
	v_add_f32_e32 v5, v5, v8
	v_cvt_i32_f32_e32 v23, v23
	v_exp_f32_e32 v5, v5
	v_cmp_nlt_f32_e32 vcc, s68, v4
	v_ldexp_f32 v5, v5, v23
	s_nop 0
	v_cndmask_b32_e32 v5, 0, v5, vcc
	v_cmp_ngt_f32_e32 vcc, s69, v4
	s_nop 1
	v_cndmask_b32_e32 v5, v95, v5, vcc
	v_add_f32_e32 v5, 1.0, v5
	v_div_scale_f32 v8, s[54:55], v5, v5, v4
	v_rcp_f32_e32 v23, v8
	v_div_scale_f32 v61, vcc, v4, v5, v4
	v_fma_f32 v65, -v8, v23, 1.0
	v_fmac_f32_e32 v23, v65, v23
	v_mul_f32_e32 v65, v61, v23
	v_fma_f32 v66, -v8, v65, v61
	v_fmac_f32_e32 v65, v66, v23
	v_fma_f32 v8, -v8, v65, v61
	v_div_fmas_f32 v8, v8, v23, v65
	v_div_fixup_f32 v4, v8, v5, v4
	ds_write_b32 v2, v4 offset:27648
	ds_write_b32 v251, v4 offset:27648
	s_waitcnt vmcnt(31)
	v_mov_b32_e32 v4, v224
	v_mul_f32_e32 v5, 0xbfb8aa3b, v4
	v_fma_f32 v8, v4, s67, -v5
	v_rndne_f32_e32 v23, v5
	v_fmac_f32_e32 v8, 0xb2a5705f, v4
	v_sub_f32_e32 v5, v5, v23
	v_add_f32_e32 v5, v5, v8
	v_cvt_i32_f32_e32 v23, v23
	v_exp_f32_e32 v5, v5
	v_cmp_nlt_f32_e32 vcc, s68, v4
	v_ldexp_f32 v5, v5, v23
	s_nop 0
	v_cndmask_b32_e32 v5, 0, v5, vcc
	v_cmp_ngt_f32_e32 vcc, s69, v4
	s_nop 1
	v_cndmask_b32_e32 v5, v95, v5, vcc
	v_add_f32_e32 v5, 1.0, v5
	v_div_scale_f32 v8, s[54:55], v5, v5, v4
	v_rcp_f32_e32 v23, v8
	v_div_scale_f32 v61, vcc, v4, v5, v4
	v_fma_f32 v65, -v8, v23, 1.0
	v_fmac_f32_e32 v23, v65, v23
	v_mul_f32_e32 v65, v61, v23
	v_fma_f32 v66, -v8, v65, v61
	v_fmac_f32_e32 v65, v66, v23
	v_fma_f32 v8, -v8, v65, v61
	v_div_fmas_f32 v8, v8, v23, v65
	v_div_fixup_f32 v4, v8, v5, v4
	ds_write_b32 v2, v4 offset:28672
	ds_write_b32 v251, v4 offset:28672
	s_waitcnt vmcnt(30)
	v_mov_b32_e32 v4, v225
	v_mul_f32_e32 v5, 0xbfb8aa3b, v4
	v_fma_f32 v8, v4, s67, -v5
	v_rndne_f32_e32 v23, v5
	v_fmac_f32_e32 v8, 0xb2a5705f, v4
	v_sub_f32_e32 v5, v5, v23
	v_add_f32_e32 v5, v5, v8
	v_cvt_i32_f32_e32 v23, v23
	v_exp_f32_e32 v5, v5
	v_cmp_nlt_f32_e32 vcc, s68, v4
	v_ldexp_f32 v5, v5, v23
	s_nop 0
	v_cndmask_b32_e32 v5, 0, v5, vcc
	v_cmp_ngt_f32_e32 vcc, s69, v4
	s_nop 1
	v_cndmask_b32_e32 v5, v95, v5, vcc
	v_add_f32_e32 v5, 1.0, v5
	v_div_scale_f32 v8, s[54:55], v5, v5, v4
	v_rcp_f32_e32 v23, v8
	v_div_scale_f32 v61, vcc, v4, v5, v4
	v_fma_f32 v65, -v8, v23, 1.0
	v_fmac_f32_e32 v23, v65, v23
	v_mul_f32_e32 v65, v61, v23
	v_fma_f32 v66, -v8, v65, v61
	v_fmac_f32_e32 v65, v66, v23
	v_fma_f32 v8, -v8, v65, v61
	v_div_fmas_f32 v8, v8, v23, v65
	v_div_fixup_f32 v4, v8, v5, v4
	ds_write_b32 v2, v4 offset:29696
	ds_write_b32 v251, v4 offset:29696
	s_waitcnt vmcnt(29)
	v_mov_b32_e32 v4, v226
	v_mul_f32_e32 v5, 0xbfb8aa3b, v4
	v_fma_f32 v8, v4, s67, -v5
	v_rndne_f32_e32 v23, v5
	v_fmac_f32_e32 v8, 0xb2a5705f, v4
	v_sub_f32_e32 v5, v5, v23
	v_add_f32_e32 v5, v5, v8
	v_cvt_i32_f32_e32 v23, v23
	v_exp_f32_e32 v5, v5
	v_cmp_nlt_f32_e32 vcc, s68, v4
	v_ldexp_f32 v5, v5, v23
	s_nop 0
	v_cndmask_b32_e32 v5, 0, v5, vcc
	v_cmp_ngt_f32_e32 vcc, s69, v4
	s_nop 1
	v_cndmask_b32_e32 v5, v95, v5, vcc
	v_add_f32_e32 v5, 1.0, v5
	v_div_scale_f32 v8, s[54:55], v5, v5, v4
	v_rcp_f32_e32 v23, v8
	v_div_scale_f32 v61, vcc, v4, v5, v4
	v_fma_f32 v65, -v8, v23, 1.0
	v_fmac_f32_e32 v23, v65, v23
	v_mul_f32_e32 v65, v61, v23
	v_fma_f32 v66, -v8, v65, v61
	v_fmac_f32_e32 v65, v66, v23
	v_fma_f32 v8, -v8, v65, v61
	v_div_fmas_f32 v8, v8, v23, v65
	v_div_fixup_f32 v4, v8, v5, v4
	ds_write_b32 v2, v4 offset:30720
	ds_write_b32 v251, v4 offset:30720
	s_waitcnt vmcnt(28)
	v_mov_b32_e32 v4, v227
	v_mul_f32_e32 v5, 0xbfb8aa3b, v4
	v_fma_f32 v8, v4, s67, -v5
	v_rndne_f32_e32 v23, v5
	v_fmac_f32_e32 v8, 0xb2a5705f, v4
	v_sub_f32_e32 v5, v5, v23
	v_add_f32_e32 v5, v5, v8
	v_cvt_i32_f32_e32 v23, v23
	v_exp_f32_e32 v5, v5
	v_cmp_nlt_f32_e32 vcc, s68, v4
	v_ldexp_f32 v5, v5, v23
	s_nop 0
	v_cndmask_b32_e32 v5, 0, v5, vcc
	v_cmp_ngt_f32_e32 vcc, s69, v4
	s_nop 1
	v_cndmask_b32_e32 v5, v95, v5, vcc
	v_add_f32_e32 v5, 1.0, v5
	v_div_scale_f32 v8, s[54:55], v5, v5, v4
	v_rcp_f32_e32 v23, v8
	v_div_scale_f32 v61, vcc, v4, v5, v4
	v_fma_f32 v65, -v8, v23, 1.0
	v_fmac_f32_e32 v23, v65, v23
	v_mul_f32_e32 v65, v61, v23
	v_fma_f32 v66, -v8, v65, v61
	v_fmac_f32_e32 v65, v66, v23
	v_fma_f32 v8, -v8, v65, v61
	v_div_fmas_f32 v8, v8, v23, v65
	v_div_fixup_f32 v4, v8, v5, v4
	ds_write_b32 v2, v4 offset:31744
	ds_write_b32 v251, v4 offset:31744
	s_waitcnt vmcnt(27)
	v_mov_b32_e32 v4, v228
	v_mul_f32_e32 v5, 0xbfb8aa3b, v4
	v_fma_f32 v8, v4, s67, -v5
	v_rndne_f32_e32 v23, v5
	v_fmac_f32_e32 v8, 0xb2a5705f, v4
	v_sub_f32_e32 v5, v5, v23
	v_add_f32_e32 v5, v5, v8
	v_cvt_i32_f32_e32 v23, v23
	v_exp_f32_e32 v5, v5
	v_cmp_nlt_f32_e32 vcc, s68, v4
	v_ldexp_f32 v5, v5, v23
	s_nop 0
	v_cndmask_b32_e32 v5, 0, v5, vcc
	v_cmp_ngt_f32_e32 vcc, s69, v4
	s_nop 1
	v_cndmask_b32_e32 v5, v95, v5, vcc
	v_add_f32_e32 v5, 1.0, v5
	v_div_scale_f32 v8, s[54:55], v5, v5, v4
	v_rcp_f32_e32 v23, v8
	v_div_scale_f32 v61, vcc, v4, v5, v4
	v_fma_f32 v65, -v8, v23, 1.0
	v_fmac_f32_e32 v23, v65, v23
	v_mul_f32_e32 v65, v61, v23
	v_fma_f32 v66, -v8, v65, v61
	v_fmac_f32_e32 v65, v66, v23
	v_fma_f32 v8, -v8, v65, v61
	v_div_fmas_f32 v8, v8, v23, v65
	v_div_fixup_f32 v4, v8, v5, v4
	ds_write_b32 v2, v4 offset:32768
	ds_write_b32 v251, v4 offset:32768
	s_waitcnt vmcnt(26)
	v_mov_b32_e32 v4, v229
	v_mul_f32_e32 v5, 0xbfb8aa3b, v4
	v_fma_f32 v8, v4, s67, -v5
	v_rndne_f32_e32 v23, v5
	v_fmac_f32_e32 v8, 0xb2a5705f, v4
	v_sub_f32_e32 v5, v5, v23
	v_add_f32_e32 v5, v5, v8
	v_cvt_i32_f32_e32 v23, v23
	v_exp_f32_e32 v5, v5
	v_cmp_nlt_f32_e32 vcc, s68, v4
	v_ldexp_f32 v5, v5, v23
	s_nop 0
	v_cndmask_b32_e32 v5, 0, v5, vcc
	v_cmp_ngt_f32_e32 vcc, s69, v4
	s_nop 1
	v_cndmask_b32_e32 v5, v95, v5, vcc
	v_add_f32_e32 v5, 1.0, v5
	v_div_scale_f32 v8, s[54:55], v5, v5, v4
	v_rcp_f32_e32 v23, v8
	v_div_scale_f32 v61, vcc, v4, v5, v4
	v_fma_f32 v65, -v8, v23, 1.0
	v_fmac_f32_e32 v23, v65, v23
	v_mul_f32_e32 v65, v61, v23
	v_fma_f32 v66, -v8, v65, v61
	v_fmac_f32_e32 v65, v66, v23
	v_fma_f32 v8, -v8, v65, v61
	v_div_fmas_f32 v8, v8, v23, v65
	v_div_fixup_f32 v4, v8, v5, v4
	ds_write_b32 v2, v4 offset:33792
	ds_write_b32 v251, v4 offset:33792
	s_waitcnt vmcnt(25)
	v_mov_b32_e32 v4, v230
	v_mul_f32_e32 v5, 0xbfb8aa3b, v4
	v_fma_f32 v8, v4, s67, -v5
	v_rndne_f32_e32 v23, v5
	v_fmac_f32_e32 v8, 0xb2a5705f, v4
	v_sub_f32_e32 v5, v5, v23
	v_add_f32_e32 v5, v5, v8
	v_cvt_i32_f32_e32 v23, v23
	v_exp_f32_e32 v5, v5
	v_cmp_nlt_f32_e32 vcc, s68, v4
	v_ldexp_f32 v5, v5, v23
	s_nop 0
	v_cndmask_b32_e32 v5, 0, v5, vcc
	v_cmp_ngt_f32_e32 vcc, s69, v4
	s_nop 1
	v_cndmask_b32_e32 v5, v95, v5, vcc
	v_add_f32_e32 v5, 1.0, v5
	v_div_scale_f32 v8, s[54:55], v5, v5, v4
	v_rcp_f32_e32 v23, v8
	v_div_scale_f32 v61, vcc, v4, v5, v4
	v_fma_f32 v65, -v8, v23, 1.0
	v_fmac_f32_e32 v23, v65, v23
	v_mul_f32_e32 v65, v61, v23
	v_fma_f32 v66, -v8, v65, v61
	v_fmac_f32_e32 v65, v66, v23
	v_fma_f32 v8, -v8, v65, v61
	v_div_fmas_f32 v8, v8, v23, v65
	v_div_fixup_f32 v4, v8, v5, v4
	ds_write_b32 v2, v4 offset:34816
	ds_write_b32 v251, v4 offset:34816
	s_waitcnt vmcnt(24)
	v_mov_b32_e32 v4, v231
	v_mul_f32_e32 v5, 0xbfb8aa3b, v4
	v_fma_f32 v8, v4, s67, -v5
	v_rndne_f32_e32 v23, v5
	v_fmac_f32_e32 v8, 0xb2a5705f, v4
	v_sub_f32_e32 v5, v5, v23
	v_add_f32_e32 v5, v5, v8
	v_cvt_i32_f32_e32 v23, v23
	v_exp_f32_e32 v5, v5
	v_cmp_nlt_f32_e32 vcc, s68, v4
	v_ldexp_f32 v5, v5, v23
	s_nop 0
	v_cndmask_b32_e32 v5, 0, v5, vcc
	v_cmp_ngt_f32_e32 vcc, s69, v4
	s_nop 1
	v_cndmask_b32_e32 v5, v95, v5, vcc
	v_add_f32_e32 v5, 1.0, v5
	v_div_scale_f32 v8, s[54:55], v5, v5, v4
	v_rcp_f32_e32 v23, v8
	v_div_scale_f32 v61, vcc, v4, v5, v4
	v_fma_f32 v65, -v8, v23, 1.0
	v_fmac_f32_e32 v23, v65, v23
	v_mul_f32_e32 v65, v61, v23
	v_fma_f32 v66, -v8, v65, v61
	v_fmac_f32_e32 v65, v66, v23
	v_fma_f32 v8, -v8, v65, v61
	v_div_fmas_f32 v8, v8, v23, v65
	v_div_fixup_f32 v4, v8, v5, v4
	ds_write_b32 v2, v4 offset:35840
	ds_write_b32 v251, v4 offset:35840
.Lsilu_done:
	s_or_b64 exec, exec, s[52:53]
	v_mov_b32_e32 v2, s72
	s_waitcnt lgkmcnt(0)
	s_barrier
	ds_read_b64 v[2:3], v2
	v_mov_b32_e32 v61, v9
	v_mov_b32_e32 v4, 0
	s_mov_b64 s[52:53], 0
	v_mov_b32_e32 v8, v81
	s_waitcnt lgkmcnt(0)
	v_add_co_u32_e32 v2, vcc, v2, v10
	v_addc_co_u32_e32 v3, vcc, v3, v11, vcc
	v_lshl_add_u64 v[2:3], v[60:61], 2, v[2:3]
	v_mov_b32_e32 v5, v4
	v_mov_b32_e32 v68, v4
	v_mov_b32_e32 v69, v4
	v_mov_b32_e32 v70, v4
	v_mov_b32_e32 v71, v4
	v_mov_b32_e32 v72, v4
	v_mov_b32_e32 v73, v4
	v_mov_b32_e32 v23, v4
	v_mov_b32_e32 v196, 0
	v_mov_b32_e32 v197, 0
	v_mov_b32_e32 v198, 0
	v_mov_b32_e32 v199, 0
	v_mov_b32_e32 v200, 0
	v_mov_b32_e32 v201, 0
	v_mov_b32_e32 v202, 0
	v_mov_b32_e32 v203, 0
	v_mov_b32_e32 v204, 0
	v_mov_b32_e32 v205, 0
	v_mov_b32_e32 v206, 0
	v_mov_b32_e32 v207, 0
	v_mov_b32_e32 v208, 0
	v_mov_b32_e32 v209, 0
	v_mov_b32_e32 v210, 0
	v_mov_b32_e32 v211, 0
	v_mov_b32_e32 v212, 0
	v_mov_b32_e32 v213, 0
	global_load_dword v174, v[194:195], off
	v_add_co_u32_e32 v194, vcc, 0x6000, v194
	v_addc_co_u32_e32 v195, vcc, 0, v195, vcc
	global_load_dword v175, v[194:195], off
	v_add_co_u32_e32 v194, vcc, 0x6000, v194
	v_addc_co_u32_e32 v195, vcc, 0, v195, vcc
	global_load_dword v176, v[194:195], off
	v_add_co_u32_e32 v194, vcc, 0x6000, v194
	v_addc_co_u32_e32 v195, vcc, 0, v195, vcc
	global_load_dword v177, v[194:195], off
	v_add_co_u32_e32 v194, vcc, 0x6000, v194
	v_addc_co_u32_e32 v195, vcc, 0, v195, vcc
	global_load_dword v178, v[194:195], off
	v_add_co_u32_e32 v194, vcc, 0x6000, v194
	v_addc_co_u32_e32 v195, vcc, 0, v195, vcc
	global_load_dword v179, v[194:195], off
	v_add_co_u32_e32 v194, vcc, 0x6000, v194
	v_addc_co_u32_e32 v195, vcc, 0, v195, vcc
	global_load_dword v180, v[194:195], off
	v_add_co_u32_e32 v194, vcc, 0x6000, v194
	v_addc_co_u32_e32 v195, vcc, 0, v195, vcc
	global_load_dword v181, v[194:195], off
	v_add_co_u32_e32 v194, vcc, 0x6000, v194
	v_addc_co_u32_e32 v195, vcc, 0, v195, vcc
	global_load_dword v182, v[194:195], off
	v_add_co_u32_e32 v194, vcc, 0x6000, v194
	v_addc_co_u32_e32 v195, vcc, 0, v195, vcc
	global_load_dword v183, v[194:195], off
	v_add_co_u32_e32 v194, vcc, 0x6000, v194
	v_addc_co_u32_e32 v195, vcc, 0, v195, vcc
	global_load_dword v184, v[194:195], off
	v_add_co_u32_e32 v194, vcc, 0x6000, v194
	v_addc_co_u32_e32 v195, vcc, 0, v195, vcc
	global_load_dword v185, v[194:195], off
	v_add_co_u32_e32 v194, vcc, 0x6000, v194
	v_addc_co_u32_e32 v195, vcc, 0, v195, vcc
	global_load_dword v186, v[194:195], off
	v_add_co_u32_e32 v194, vcc, 0x6000, v194
	v_addc_co_u32_e32 v195, vcc, 0, v195, vcc
	global_load_dword v187, v[194:195], off
	v_add_co_u32_e32 v194, vcc, 0x6000, v194
	v_addc_co_u32_e32 v195, vcc, 0, v195, vcc
	global_load_dword v188, v[194:195], off
	v_add_co_u32_e32 v194, vcc, 0x6000, v194
	v_addc_co_u32_e32 v195, vcc, 0, v195, vcc
	global_load_dword v189, v[194:195], off
	v_add_co_u32_e32 v194, vcc, 0x6000, v194
	v_addc_co_u32_e32 v195, vcc, 0, v195, vcc
	global_load_dword v190, v[194:195], off
	v_add_co_u32_e32 v194, vcc, 0x6000, v194
	v_addc_co_u32_e32 v195, vcc, 0, v195, vcc
	global_load_dword v191, v[194:195], off
	v_add_co_u32_e32 v194, vcc, 0x6000, v194
	v_addc_co_u32_e32 v195, vcc, 0, v195, vcc
	global_load_dword v192, v[194:195], off
	v_add_co_u32_e32 v194, vcc, 0x6000, v194
	v_addc_co_u32_e32 v195, vcc, 0, v195, vcc
	global_load_dword v193, v[194:195], off
	v_add_co_u32_e32 v194, vcc, 0x6000, v194
	v_addc_co_u32_e32 v195, vcc, 0, v195, vcc
	ds_read_b128 v[98:101], v8 offset:4096
	ds_read_b128 v[102:105], v8 offset:8192
	ds_read_b128 v[106:109], v8 offset:12288
	ds_read_b128 v[110:113], v8 offset:16384
	ds_read_b128 v[114:117], v8 offset:20480
	ds_read_b128 v[118:121], v8 offset:24576
	ds_read_b128 v[122:125], v8 offset:28672
	ds_read_b128 v[126:129], v8
	ds_read_b128 v[134:137], v8 offset:32768
	v_add_u32_e32 v8, 16, v8
	s_waitcnt vmcnt(40) lgkmcnt(0)
	v_pk_fma_f32 v[196:197], v[150:151], v[126:127], v[196:197]
	v_pk_fma_f32 v[198:199], v[150:151], v[98:99], v[198:199]
	v_pk_fma_f32 v[200:201], v[150:151], v[102:103], v[200:201]
	v_pk_fma_f32 v[202:203], v[150:151], v[106:107], v[202:203]
	v_pk_fma_f32 v[204:205], v[150:151], v[110:111], v[204:205]
	v_pk_fma_f32 v[206:207], v[150:151], v[114:115], v[206:207]
	v_pk_fma_f32 v[208:209], v[150:151], v[118:119], v[208:209]
	v_pk_fma_f32 v[210:211], v[150:151], v[122:123], v[210:211]
	v_pk_fma_f32 v[212:213], v[150:151], v[134:135], v[212:213]
	v_pk_fma_f32 v[196:197], v[152:153], v[128:129], v[196:197]
	v_pk_fma_f32 v[198:199], v[152:153], v[100:101], v[198:199]
	v_pk_fma_f32 v[200:201], v[152:153], v[104:105], v[200:201]
	v_pk_fma_f32 v[202:203], v[152:153], v[108:109], v[202:203]
	v_pk_fma_f32 v[204:205], v[152:153], v[112:113], v[204:205]
	v_pk_fma_f32 v[206:207], v[152:153], v[116:117], v[206:207]
	v_pk_fma_f32 v[208:209], v[152:153], v[120:121], v[208:209]
	v_pk_fma_f32 v[210:211], v[152:153], v[124:125], v[210:211]
	v_pk_fma_f32 v[212:213], v[152:153], v[136:137], v[212:213]
	global_load_dword v150, v[194:195], off
	v_add_co_u32_e32 v194, vcc, 0x6000, v194
	v_addc_co_u32_e32 v195, vcc, 0, v195, vcc
	global_load_dword v151, v[194:195], off
	v_add_co_u32_e32 v194, vcc, 0x6000, v194
	v_addc_co_u32_e32 v195, vcc, 0, v195, vcc
	global_load_dword v152, v[194:195], off
	v_add_co_u32_e32 v194, vcc, 0x6000, v194
	v_addc_co_u32_e32 v195, vcc, 0, v195, vcc
	global_load_dword v153, v[194:195], off
	v_add_co_u32_e32 v194, vcc, 0x6000, v194
	v_addc_co_u32_e32 v195, vcc, 0, v195, vcc
	ds_read_b128 v[98:101], v8 offset:4096
	ds_read_b128 v[102:105], v8 offset:8192
	ds_read_b128 v[106:109], v8 offset:12288
	ds_read_b128 v[110:113], v8 offset:16384
	ds_read_b128 v[114:117], v8 offset:20480
	ds_read_b128 v[118:121], v8 offset:24576
	ds_read_b128 v[122:125], v8 offset:28672
	ds_read_b128 v[126:129], v8
	ds_read_b128 v[134:137], v8 offset:32768
	v_add_u32_e32 v8, 16, v8
	s_waitcnt vmcnt(40) lgkmcnt(0)
	v_pk_fma_f32 v[196:197], v[154:155], v[126:127], v[196:197]
	v_pk_fma_f32 v[198:199], v[154:155], v[98:99], v[198:199]
	v_pk_fma_f32 v[200:201], v[154:155], v[102:103], v[200:201]
	v_pk_fma_f32 v[202:203], v[154:155], v[106:107], v[202:203]
	v_pk_fma_f32 v[204:205], v[154:155], v[110:111], v[204:205]
	v_pk_fma_f32 v[206:207], v[154:155], v[114:115], v[206:207]
	v_pk_fma_f32 v[208:209], v[154:155], v[118:119], v[208:209]
	v_pk_fma_f32 v[210:211], v[154:155], v[122:123], v[210:211]
	v_pk_fma_f32 v[212:213], v[154:155], v[134:135], v[212:213]
	v_pk_fma_f32 v[196:197], v[156:157], v[128:129], v[196:197]
	v_pk_fma_f32 v[198:199], v[156:157], v[100:101], v[198:199]
	v_pk_fma_f32 v[200:201], v[156:157], v[104:105], v[200:201]
	v_pk_fma_f32 v[202:203], v[156:157], v[108:109], v[202:203]
	v_pk_fma_f32 v[204:205], v[156:157], v[112:113], v[204:205]
	v_pk_fma_f32 v[206:207], v[156:157], v[116:117], v[206:207]
	v_pk_fma_f32 v[208:209], v[156:157], v[120:121], v[208:209]
	v_pk_fma_f32 v[210:211], v[156:157], v[124:125], v[210:211]
	v_pk_fma_f32 v[212:213], v[156:157], v[136:137], v[212:213]
	global_load_dword v154, v[194:195], off
	v_add_co_u32_e32 v194, vcc, 0x6000, v194
	v_addc_co_u32_e32 v195, vcc, 0, v195, vcc
	global_load_dword v155, v[194:195], off
	v_add_co_u32_e32 v194, vcc, 0x6000, v194
	v_addc_co_u32_e32 v195, vcc, 0, v195, vcc
	global_load_dword v156, v[194:195], off
	v_add_co_u32_e32 v194, vcc, 0x6000, v194
	v_addc_co_u32_e32 v195, vcc, 0, v195, vcc
	global_load_dword v157, v[194:195], off
	v_add_co_u32_e32 v194, vcc, 0x6000, v194
	v_addc_co_u32_e32 v195, vcc, 0, v195, vcc
	ds_read_b128 v[98:101], v8 offset:4096
	ds_read_b128 v[102:105], v8 offset:8192
	ds_read_b128 v[106:109], v8 offset:12288
	ds_read_b128 v[110:113], v8 offset:16384
	ds_read_b128 v[114:117], v8 offset:20480
	ds_read_b128 v[118:121], v8 offset:24576
	ds_read_b128 v[122:125], v8 offset:28672
	ds_read_b128 v[126:129], v8
	ds_read_b128 v[134:137], v8 offset:32768
	v_add_u32_e32 v8, 16, v8
	s_waitcnt vmcnt(40) lgkmcnt(0)
	v_pk_fma_f32 v[196:197], v[158:159], v[126:127], v[196:197]
	v_pk_fma_f32 v[198:199], v[158:159], v[98:99], v[198:199]
	v_pk_fma_f32 v[200:201], v[158:159], v[102:103], v[200:201]
	v_pk_fma_f32 v[202:203], v[158:159], v[106:107], v[202:203]
	v_pk_fma_f32 v[204:205], v[158:159], v[110:111], v[204:205]
	v_pk_fma_f32 v[206:207], v[158:159], v[114:115], v[206:207]
	v_pk_fma_f32 v[208:209], v[158:159], v[118:119], v[208:209]
	v_pk_fma_f32 v[210:211], v[158:159], v[122:123], v[210:211]
	v_pk_fma_f32 v[212:213], v[158:159], v[134:135], v[212:213]
	v_pk_fma_f32 v[196:197], v[160:161], v[128:129], v[196:197]
	v_pk_fma_f32 v[198:199], v[160:161], v[100:101], v[198:199]
	v_pk_fma_f32 v[200:201], v[160:161], v[104:105], v[200:201]
	v_pk_fma_f32 v[202:203], v[160:161], v[108:109], v[202:203]
	v_pk_fma_f32 v[204:205], v[160:161], v[112:113], v[204:205]
	v_pk_fma_f32 v[206:207], v[160:161], v[116:117], v[206:207]
	v_pk_fma_f32 v[208:209], v[160:161], v[120:121], v[208:209]
	v_pk_fma_f32 v[210:211], v[160:161], v[124:125], v[210:211]
	v_pk_fma_f32 v[212:213], v[160:161], v[136:137], v[212:213]
	global_load_dword v158, v[194:195], off
	v_add_co_u32_e32 v194, vcc, 0x6000, v194
	v_addc_co_u32_e32 v195, vcc, 0, v195, vcc
	global_load_dword v159, v[194:195], off
	v_add_co_u32_e32 v194, vcc, 0x6000, v194
	v_addc_co_u32_e32 v195, vcc, 0, v195, vcc
	global_load_dword v160, v[194:195], off
	v_add_co_u32_e32 v194, vcc, 0x6000, v194
	v_addc_co_u32_e32 v195, vcc, 0, v195, vcc
	global_load_dword v161, v[194:195], off
	v_add_co_u32_e32 v194, vcc, 0x6000, v194
	v_addc_co_u32_e32 v195, vcc, 0, v195, vcc
	ds_read_b128 v[98:101], v8 offset:4096
	ds_read_b128 v[102:105], v8 offset:8192
	ds_read_b128 v[106:109], v8 offset:12288
	ds_read_b128 v[110:113], v8 offset:16384
	ds_read_b128 v[114:117], v8 offset:20480
	ds_read_b128 v[118:121], v8 offset:24576
	ds_read_b128 v[122:125], v8 offset:28672
	ds_read_b128 v[126:129], v8
	ds_read_b128 v[134:137], v8 offset:32768
	v_add_u32_e32 v8, 16, v8
	s_waitcnt vmcnt(40) lgkmcnt(0)
	v_pk_fma_f32 v[196:197], v[162:163], v[126:127], v[196:197]
	v_pk_fma_f32 v[198:199], v[162:163], v[98:99], v[198:199]
	v_pk_fma_f32 v[200:201], v[162:163], v[102:103], v[200:201]
	v_pk_fma_f32 v[202:203], v[162:163], v[106:107], v[202:203]
	v_pk_fma_f32 v[204:205], v[162:163], v[110:111], v[204:205]
	v_pk_fma_f32 v[206:207], v[162:163], v[114:115], v[206:207]
	v_pk_fma_f32 v[208:209], v[162:163], v[118:119], v[208:209]
	v_pk_fma_f32 v[210:211], v[162:163], v[122:123], v[210:211]
	v_pk_fma_f32 v[212:213], v[162:163], v[134:135], v[212:213]
	v_pk_fma_f32 v[196:197], v[164:165], v[128:129], v[196:197]
	v_pk_fma_f32 v[198:199], v[164:165], v[100:101], v[198:199]
	v_pk_fma_f32 v[200:201], v[164:165], v[104:105], v[200:201]
	v_pk_fma_f32 v[202:203], v[164:165], v[108:109], v[202:203]
	v_pk_fma_f32 v[204:205], v[164:165], v[112:113], v[204:205]
	v_pk_fma_f32 v[206:207], v[164:165], v[116:117], v[206:207]
	v_pk_fma_f32 v[208:209], v[164:165], v[120:121], v[208:209]
	v_pk_fma_f32 v[210:211], v[164:165], v[124:125], v[210:211]
	v_pk_fma_f32 v[212:213], v[164:165], v[136:137], v[212:213]
	global_load_dword v162, v[194:195], off
	v_add_co_u32_e32 v194, vcc, 0x6000, v194
	v_addc_co_u32_e32 v195, vcc, 0, v195, vcc
	global_load_dword v163, v[194:195], off
	v_add_co_u32_e32 v194, vcc, 0x6000, v194
	v_addc_co_u32_e32 v195, vcc, 0, v195, vcc
	global_load_dword v164, v[194:195], off
	v_add_co_u32_e32 v194, vcc, 0x6000, v194
	v_addc_co_u32_e32 v195, vcc, 0, v195, vcc
	global_load_dword v165, v[194:195], off
	v_add_co_u32_e32 v194, vcc, 0x6000, v194
	v_addc_co_u32_e32 v195, vcc, 0, v195, vcc
	ds_read_b128 v[98:101], v8 offset:4096
	ds_read_b128 v[102:105], v8 offset:8192
	ds_read_b128 v[106:109], v8 offset:12288
	ds_read_b128 v[110:113], v8 offset:16384
	ds_read_b128 v[114:117], v8 offset:20480
	ds_read_b128 v[118:121], v8 offset:24576
	ds_read_b128 v[122:125], v8 offset:28672
	ds_read_b128 v[126:129], v8
	ds_read_b128 v[134:137], v8 offset:32768
	v_add_u32_e32 v8, 16, v8
	s_waitcnt vmcnt(40) lgkmcnt(0)
	v_pk_fma_f32 v[196:197], v[166:167], v[126:127], v[196:197]
	v_pk_fma_f32 v[198:199], v[166:167], v[98:99], v[198:199]
	v_pk_fma_f32 v[200:201], v[166:167], v[102:103], v[200:201]
	v_pk_fma_f32 v[202:203], v[166:167], v[106:107], v[202:203]
	v_pk_fma_f32 v[204:205], v[166:167], v[110:111], v[204:205]
	v_pk_fma_f32 v[206:207], v[166:167], v[114:115], v[206:207]
	v_pk_fma_f32 v[208:209], v[166:167], v[118:119], v[208:209]
	v_pk_fma_f32 v[210:211], v[166:167], v[122:123], v[210:211]
	v_pk_fma_f32 v[212:213], v[166:167], v[134:135], v[212:213]
	v_pk_fma_f32 v[196:197], v[168:169], v[128:129], v[196:197]
	v_pk_fma_f32 v[198:199], v[168:169], v[100:101], v[198:199]
	v_pk_fma_f32 v[200:201], v[168:169], v[104:105], v[200:201]
	v_pk_fma_f32 v[202:203], v[168:169], v[108:109], v[202:203]
	v_pk_fma_f32 v[204:205], v[168:169], v[112:113], v[204:205]
	v_pk_fma_f32 v[206:207], v[168:169], v[116:117], v[206:207]
	v_pk_fma_f32 v[208:209], v[168:169], v[120:121], v[208:209]
	v_pk_fma_f32 v[210:211], v[168:169], v[124:125], v[210:211]
	v_pk_fma_f32 v[212:213], v[168:169], v[136:137], v[212:213]
	global_load_dword v166, v[194:195], off
	v_add_co_u32_e32 v194, vcc, 0x6000, v194
	v_addc_co_u32_e32 v195, vcc, 0, v195, vcc
	global_load_dword v167, v[194:195], off
	v_add_co_u32_e32 v194, vcc, 0x6000, v194
	v_addc_co_u32_e32 v195, vcc, 0, v195, vcc
	global_load_dword v168, v[194:195], off
	v_add_co_u32_e32 v194, vcc, 0x6000, v194
	v_addc_co_u32_e32 v195, vcc, 0, v195, vcc
	global_load_dword v169, v[194:195], off
	v_add_co_u32_e32 v194, vcc, 0x6000, v194
	v_addc_co_u32_e32 v195, vcc, 0, v195, vcc
	ds_read_b128 v[98:101], v8 offset:4096
	ds_read_b128 v[102:105], v8 offset:8192
	ds_read_b128 v[106:109], v8 offset:12288
	ds_read_b128 v[110:113], v8 offset:16384
	ds_read_b128 v[114:117], v8 offset:20480
	ds_read_b128 v[118:121], v8 offset:24576
	ds_read_b128 v[122:125], v8 offset:28672
	ds_read_b128 v[126:129], v8
	ds_read_b128 v[134:137], v8 offset:32768
	v_add_u32_e32 v8, 16, v8
	s_waitcnt vmcnt(40) lgkmcnt(0)
	v_pk_fma_f32 v[196:197], v[170:171], v[126:127], v[196:197]
	v_pk_fma_f32 v[198:199], v[170:171], v[98:99], v[198:199]
	v_pk_fma_f32 v[200:201], v[170:171], v[102:103], v[200:201]
	v_pk_fma_f32 v[202:203], v[170:171], v[106:107], v[202:203]
	v_pk_fma_f32 v[204:205], v[170:171], v[110:111], v[204:205]
	v_pk_fma_f32 v[206:207], v[170:171], v[114:115], v[206:207]
	v_pk_fma_f32 v[208:209], v[170:171], v[118:119], v[208:209]
	v_pk_fma_f32 v[210:211], v[170:171], v[122:123], v[210:211]
	v_pk_fma_f32 v[212:213], v[170:171], v[134:135], v[212:213]
	v_pk_fma_f32 v[196:197], v[172:173], v[128:129], v[196:197]
	v_pk_fma_f32 v[198:199], v[172:173], v[100:101], v[198:199]
	v_pk_fma_f32 v[200:201], v[172:173], v[104:105], v[200:201]
	v_pk_fma_f32 v[202:203], v[172:173], v[108:109], v[202:203]
	v_pk_fma_f32 v[204:205], v[172:173], v[112:113], v[204:205]
	v_pk_fma_f32 v[206:207], v[172:173], v[116:117], v[206:207]
	v_pk_fma_f32 v[208:209], v[172:173], v[120:121], v[208:209]
	v_pk_fma_f32 v[210:211], v[172:173], v[124:125], v[210:211]
	v_pk_fma_f32 v[212:213], v[172:173], v[136:137], v[212:213]
	global_load_dword v170, v[194:195], off
	v_add_co_u32_e32 v194, vcc, 0x6000, v194
	v_addc_co_u32_e32 v195, vcc, 0, v195, vcc
	global_load_dword v171, v[194:195], off
	v_add_co_u32_e32 v194, vcc, 0x6000, v194
	v_addc_co_u32_e32 v195, vcc, 0, v195, vcc
	global_load_dword v172, v[194:195], off
	v_add_co_u32_e32 v194, vcc, 0x6000, v194
	v_addc_co_u32_e32 v195, vcc, 0, v195, vcc
	global_load_dword v173, v[194:195], off
	v_add_co_u32_e32 v194, vcc, 0x6000, v194
	v_addc_co_u32_e32 v195, vcc, 0, v195, vcc
	ds_read_b128 v[98:101], v8 offset:4096
	ds_read_b128 v[102:105], v8 offset:8192
	ds_read_b128 v[106:109], v8 offset:12288
	ds_read_b128 v[110:113], v8 offset:16384
	ds_read_b128 v[114:117], v8 offset:20480
	ds_read_b128 v[118:121], v8 offset:24576
	ds_read_b128 v[122:125], v8 offset:28672
	ds_read_b128 v[126:129], v8
	ds_read_b128 v[134:137], v8 offset:32768
	v_add_u32_e32 v8, 16, v8
	s_waitcnt vmcnt(40) lgkmcnt(0)
	v_pk_fma_f32 v[196:197], v[174:175], v[126:127], v[196:197]
	v_pk_fma_f32 v[198:199], v[174:175], v[98:99], v[198:199]
	v_pk_fma_f32 v[200:201], v[174:175], v[102:103], v[200:201]
	v_pk_fma_f32 v[202:203], v[174:175], v[106:107], v[202:203]
	v_pk_fma_f32 v[204:205], v[174:175], v[110:111], v[204:205]
	v_pk_fma_f32 v[206:207], v[174:175], v[114:115], v[206:207]
	v_pk_fma_f32 v[208:209], v[174:175], v[118:119], v[208:209]
	v_pk_fma_f32 v[210:211], v[174:175], v[122:123], v[210:211]
	v_pk_fma_f32 v[212:213], v[174:175], v[134:135], v[212:213]
	v_pk_fma_f32 v[196:197], v[176:177], v[128:129], v[196:197]
	v_pk_fma_f32 v[198:199], v[176:177], v[100:101], v[198:199]
	v_pk_fma_f32 v[200:201], v[176:177], v[104:105], v[200:201]
	v_pk_fma_f32 v[202:203], v[176:177], v[108:109], v[202:203]
	v_pk_fma_f32 v[204:205], v[176:177], v[112:113], v[204:205]
	v_pk_fma_f32 v[206:207], v[176:177], v[116:117], v[206:207]
	v_pk_fma_f32 v[208:209], v[176:177], v[120:121], v[208:209]
	v_pk_fma_f32 v[210:211], v[176:177], v[124:125], v[210:211]
	v_pk_fma_f32 v[212:213], v[176:177], v[136:137], v[212:213]
	global_load_dword v174, v[194:195], off
	v_add_co_u32_e32 v194, vcc, 0x6000, v194
	v_addc_co_u32_e32 v195, vcc, 0, v195, vcc
	global_load_dword v175, v[194:195], off
	v_add_co_u32_e32 v194, vcc, 0x6000, v194
	v_addc_co_u32_e32 v195, vcc, 0, v195, vcc
	global_load_dword v176, v[194:195], off
	v_add_co_u32_e32 v194, vcc, 0x6000, v194
	v_addc_co_u32_e32 v195, vcc, 0, v195, vcc
	global_load_dword v177, v[194:195], off
	v_add_co_u32_e32 v194, vcc, 0x6000, v194
	v_addc_co_u32_e32 v195, vcc, 0, v195, vcc
	ds_read_b128 v[98:101], v8 offset:4096
	ds_read_b128 v[102:105], v8 offset:8192
	ds_read_b128 v[106:109], v8 offset:12288
	ds_read_b128 v[110:113], v8 offset:16384
	ds_read_b128 v[114:117], v8 offset:20480
	ds_read_b128 v[118:121], v8 offset:24576
	ds_read_b128 v[122:125], v8 offset:28672
	ds_read_b128 v[126:129], v8
	ds_read_b128 v[134:137], v8 offset:32768
	v_add_u32_e32 v8, 16, v8
	s_waitcnt vmcnt(40) lgkmcnt(0)
	v_pk_fma_f32 v[196:197], v[178:179], v[126:127], v[196:197]
	v_pk_fma_f32 v[198:199], v[178:179], v[98:99], v[198:199]
	v_pk_fma_f32 v[200:201], v[178:179], v[102:103], v[200:201]
	v_pk_fma_f32 v[202:203], v[178:179], v[106:107], v[202:203]
	v_pk_fma_f32 v[204:205], v[178:179], v[110:111], v[204:205]
	v_pk_fma_f32 v[206:207], v[178:179], v[114:115], v[206:207]
	v_pk_fma_f32 v[208:209], v[178:179], v[118:119], v[208:209]
	v_pk_fma_f32 v[210:211], v[178:179], v[122:123], v[210:211]
	v_pk_fma_f32 v[212:213], v[178:179], v[134:135], v[212:213]
	v_pk_fma_f32 v[196:197], v[180:181], v[128:129], v[196:197]
	v_pk_fma_f32 v[198:199], v[180:181], v[100:101], v[198:199]
	v_pk_fma_f32 v[200:201], v[180:181], v[104:105], v[200:201]
	v_pk_fma_f32 v[202:203], v[180:181], v[108:109], v[202:203]
	v_pk_fma_f32 v[204:205], v[180:181], v[112:113], v[204:205]
	v_pk_fma_f32 v[206:207], v[180:181], v[116:117], v[206:207]
	v_pk_fma_f32 v[208:209], v[180:181], v[120:121], v[208:209]
	v_pk_fma_f32 v[210:211], v[180:181], v[124:125], v[210:211]
	v_pk_fma_f32 v[212:213], v[180:181], v[136:137], v[212:213]
	global_load_dword v178, v[194:195], off
	v_add_co_u32_e32 v194, vcc, 0x6000, v194
	v_addc_co_u32_e32 v195, vcc, 0, v195, vcc
	global_load_dword v179, v[194:195], off
	v_add_co_u32_e32 v194, vcc, 0x6000, v194
	v_addc_co_u32_e32 v195, vcc, 0, v195, vcc
	global_load_dword v180, v[194:195], off
	v_add_co_u32_e32 v194, vcc, 0x6000, v194
	v_addc_co_u32_e32 v195, vcc, 0, v195, vcc
	global_load_dword v181, v[194:195], off
	v_add_co_u32_e32 v194, vcc, 0x6000, v194
	v_addc_co_u32_e32 v195, vcc, 0, v195, vcc
	ds_read_b128 v[98:101], v8 offset:4096
	ds_read_b128 v[102:105], v8 offset:8192
	ds_read_b128 v[106:109], v8 offset:12288
	ds_read_b128 v[110:113], v8 offset:16384
	ds_read_b128 v[114:117], v8 offset:20480
	ds_read_b128 v[118:121], v8 offset:24576
	ds_read_b128 v[122:125], v8 offset:28672
	ds_read_b128 v[126:129], v8
	ds_read_b128 v[134:137], v8 offset:32768
	v_add_u32_e32 v8, 16, v8
	s_waitcnt vmcnt(40) lgkmcnt(0)
	v_pk_fma_f32 v[196:197], v[182:183], v[126:127], v[196:197]
	v_pk_fma_f32 v[198:199], v[182:183], v[98:99], v[198:199]
	v_pk_fma_f32 v[200:201], v[182:183], v[102:103], v[200:201]
	v_pk_fma_f32 v[202:203], v[182:183], v[106:107], v[202:203]
	v_pk_fma_f32 v[204:205], v[182:183], v[110:111], v[204:205]
	v_pk_fma_f32 v[206:207], v[182:183], v[114:115], v[206:207]
	v_pk_fma_f32 v[208:209], v[182:183], v[118:119], v[208:209]
	v_pk_fma_f32 v[210:211], v[182:183], v[122:123], v[210:211]
	v_pk_fma_f32 v[212:213], v[182:183], v[134:135], v[212:213]
	v_pk_fma_f32 v[196:197], v[184:185], v[128:129], v[196:197]
	v_pk_fma_f32 v[198:199], v[184:185], v[100:101], v[198:199]
	v_pk_fma_f32 v[200:201], v[184:185], v[104:105], v[200:201]
	v_pk_fma_f32 v[202:203], v[184:185], v[108:109], v[202:203]
	v_pk_fma_f32 v[204:205], v[184:185], v[112:113], v[204:205]
	v_pk_fma_f32 v[206:207], v[184:185], v[116:117], v[206:207]
	v_pk_fma_f32 v[208:209], v[184:185], v[120:121], v[208:209]
	v_pk_fma_f32 v[210:211], v[184:185], v[124:125], v[210:211]
	v_pk_fma_f32 v[212:213], v[184:185], v[136:137], v[212:213]
	global_load_dword v182, v[194:195], off
	v_add_co_u32_e32 v194, vcc, 0x6000, v194
	v_addc_co_u32_e32 v195, vcc, 0, v195, vcc
	global_load_dword v183, v[194:195], off
	v_add_co_u32_e32 v194, vcc, 0x6000, v194
	v_addc_co_u32_e32 v195, vcc, 0, v195, vcc
	global_load_dword v184, v[194:195], off
	v_add_co_u32_e32 v194, vcc, 0x6000, v194
	v_addc_co_u32_e32 v195, vcc, 0, v195, vcc
	global_load_dword v185, v[194:195], off
	v_add_co_u32_e32 v194, vcc, 0x6000, v194
	v_addc_co_u32_e32 v195, vcc, 0, v195, vcc
	ds_read_b128 v[98:101], v8 offset:4096
	ds_read_b128 v[102:105], v8 offset:8192
	ds_read_b128 v[106:109], v8 offset:12288
	ds_read_b128 v[110:113], v8 offset:16384
	ds_read_b128 v[114:117], v8 offset:20480
	ds_read_b128 v[118:121], v8 offset:24576
	ds_read_b128 v[122:125], v8 offset:28672
	ds_read_b128 v[126:129], v8
	ds_read_b128 v[134:137], v8 offset:32768
	v_add_u32_e32 v8, 16, v8
	s_waitcnt vmcnt(40) lgkmcnt(0)
	v_pk_fma_f32 v[196:197], v[186:187], v[126:127], v[196:197]
	v_pk_fma_f32 v[198:199], v[186:187], v[98:99], v[198:199]
	v_pk_fma_f32 v[200:201], v[186:187], v[102:103], v[200:201]
	v_pk_fma_f32 v[202:203], v[186:187], v[106:107], v[202:203]
	v_pk_fma_f32 v[204:205], v[186:187], v[110:111], v[204:205]
	v_pk_fma_f32 v[206:207], v[186:187], v[114:115], v[206:207]
	v_pk_fma_f32 v[208:209], v[186:187], v[118:119], v[208:209]
	v_pk_fma_f32 v[210:211], v[186:187], v[122:123], v[210:211]
	v_pk_fma_f32 v[212:213], v[186:187], v[134:135], v[212:213]
	v_pk_fma_f32 v[196:197], v[188:189], v[128:129], v[196:197]
	v_pk_fma_f32 v[198:199], v[188:189], v[100:101], v[198:199]
	v_pk_fma_f32 v[200:201], v[188:189], v[104:105], v[200:201]
	v_pk_fma_f32 v[202:203], v[188:189], v[108:109], v[202:203]
	v_pk_fma_f32 v[204:205], v[188:189], v[112:113], v[204:205]
	v_pk_fma_f32 v[206:207], v[188:189], v[116:117], v[206:207]
	v_pk_fma_f32 v[208:209], v[188:189], v[120:121], v[208:209]
	v_pk_fma_f32 v[210:211], v[188:189], v[124:125], v[210:211]
	v_pk_fma_f32 v[212:213], v[188:189], v[136:137], v[212:213]
	global_load_dword v186, v[194:195], off
	v_add_co_u32_e32 v194, vcc, 0x6000, v194
	v_addc_co_u32_e32 v195, vcc, 0, v195, vcc
	global_load_dword v187, v[194:195], off
	v_add_co_u32_e32 v194, vcc, 0x6000, v194
	v_addc_co_u32_e32 v195, vcc, 0, v195, vcc
	global_load_dword v188, v[194:195], off
	v_add_co_u32_e32 v194, vcc, 0x6000, v194
	v_addc_co_u32_e32 v195, vcc, 0, v195, vcc
	global_load_dword v189, v[194:195], off
	v_add_co_u32_e32 v194, vcc, 0x6000, v194
	v_addc_co_u32_e32 v195, vcc, 0, v195, vcc
	ds_read_b128 v[98:101], v8 offset:4096
	ds_read_b128 v[102:105], v8 offset:8192
	ds_read_b128 v[106:109], v8 offset:12288
	ds_read_b128 v[110:113], v8 offset:16384
	ds_read_b128 v[114:117], v8 offset:20480
	ds_read_b128 v[118:121], v8 offset:24576
	ds_read_b128 v[122:125], v8 offset:28672
	ds_read_b128 v[126:129], v8
	ds_read_b128 v[134:137], v8 offset:32768
	v_add_u32_e32 v8, 16, v8
	s_waitcnt vmcnt(40) lgkmcnt(0)
	v_pk_fma_f32 v[196:197], v[190:191], v[126:127], v[196:197]
	v_pk_fma_f32 v[198:199], v[190:191], v[98:99], v[198:199]
	v_pk_fma_f32 v[200:201], v[190:191], v[102:103], v[200:201]
	v_pk_fma_f32 v[202:203], v[190:191], v[106:107], v[202:203]
	v_pk_fma_f32 v[204:205], v[190:191], v[110:111], v[204:205]
	v_pk_fma_f32 v[206:207], v[190:191], v[114:115], v[206:207]
	v_pk_fma_f32 v[208:209], v[190:191], v[118:119], v[208:209]
	v_pk_fma_f32 v[210:211], v[190:191], v[122:123], v[210:211]
	v_pk_fma_f32 v[212:213], v[190:191], v[134:135], v[212:213]
	v_pk_fma_f32 v[196:197], v[192:193], v[128:129], v[196:197]
	v_pk_fma_f32 v[198:199], v[192:193], v[100:101], v[198:199]
	v_pk_fma_f32 v[200:201], v[192:193], v[104:105], v[200:201]
	v_pk_fma_f32 v[202:203], v[192:193], v[108:109], v[202:203]
	v_pk_fma_f32 v[204:205], v[192:193], v[112:113], v[204:205]
	v_pk_fma_f32 v[206:207], v[192:193], v[116:117], v[206:207]
	v_pk_fma_f32 v[208:209], v[192:193], v[120:121], v[208:209]
	v_pk_fma_f32 v[210:211], v[192:193], v[124:125], v[210:211]
	v_pk_fma_f32 v[212:213], v[192:193], v[136:137], v[212:213]
	global_load_dword v190, v[194:195], off
	v_add_co_u32_e32 v194, vcc, 0x6000, v194
	v_addc_co_u32_e32 v195, vcc, 0, v195, vcc
	global_load_dword v191, v[194:195], off
	v_add_co_u32_e32 v194, vcc, 0x6000, v194
	v_addc_co_u32_e32 v195, vcc, 0, v195, vcc
	global_load_dword v192, v[194:195], off
	v_add_co_u32_e32 v194, vcc, 0x6000, v194
	v_addc_co_u32_e32 v195, vcc, 0, v195, vcc
	global_load_dword v193, v[194:195], off
	v_add_co_u32_e32 v194, vcc, 0x6000, v194
	v_addc_co_u32_e32 v195, vcc, 0, v195, vcc
	ds_read_b128 v[98:101], v8 offset:4096
	ds_read_b128 v[102:105], v8 offset:8192
	ds_read_b128 v[106:109], v8 offset:12288
	ds_read_b128 v[110:113], v8 offset:16384
	ds_read_b128 v[114:117], v8 offset:20480
	ds_read_b128 v[118:121], v8 offset:24576
	ds_read_b128 v[122:125], v8 offset:28672
	ds_read_b128 v[126:129], v8
	ds_read_b128 v[134:137], v8 offset:32768
	v_add_u32_e32 v8, 16, v8
	s_waitcnt vmcnt(40) lgkmcnt(0)
	v_pk_fma_f32 v[196:197], v[150:151], v[126:127], v[196:197]
	v_pk_fma_f32 v[198:199], v[150:151], v[98:99], v[198:199]
	v_pk_fma_f32 v[200:201], v[150:151], v[102:103], v[200:201]
	v_pk_fma_f32 v[202:203], v[150:151], v[106:107], v[202:203]
	v_pk_fma_f32 v[204:205], v[150:151], v[110:111], v[204:205]
	v_pk_fma_f32 v[206:207], v[150:151], v[114:115], v[206:207]
	v_pk_fma_f32 v[208:209], v[150:151], v[118:119], v[208:209]
	v_pk_fma_f32 v[210:211], v[150:151], v[122:123], v[210:211]
	v_pk_fma_f32 v[212:213], v[150:151], v[134:135], v[212:213]
	v_pk_fma_f32 v[196:197], v[152:153], v[128:129], v[196:197]
	v_pk_fma_f32 v[198:199], v[152:153], v[100:101], v[198:199]
	v_pk_fma_f32 v[200:201], v[152:153], v[104:105], v[200:201]
	v_pk_fma_f32 v[202:203], v[152:153], v[108:109], v[202:203]
	v_pk_fma_f32 v[204:205], v[152:153], v[112:113], v[204:205]
	v_pk_fma_f32 v[206:207], v[152:153], v[116:117], v[206:207]
	v_pk_fma_f32 v[208:209], v[152:153], v[120:121], v[208:209]
	v_pk_fma_f32 v[210:211], v[152:153], v[124:125], v[210:211]
	v_pk_fma_f32 v[212:213], v[152:153], v[136:137], v[212:213]
	global_load_dword v150, v[194:195], off
	v_add_co_u32_e32 v194, vcc, 0x6000, v194
	v_addc_co_u32_e32 v195, vcc, 0, v195, vcc
	global_load_dword v151, v[194:195], off
	v_add_co_u32_e32 v194, vcc, 0x6000, v194
	v_addc_co_u32_e32 v195, vcc, 0, v195, vcc
	global_load_dword v152, v[194:195], off
	v_add_co_u32_e32 v194, vcc, 0x6000, v194
	v_addc_co_u32_e32 v195, vcc, 0, v195, vcc
	global_load_dword v153, v[194:195], off
	v_add_co_u32_e32 v194, vcc, 0x6000, v194
	v_addc_co_u32_e32 v195, vcc, 0, v195, vcc
	ds_read_b128 v[98:101], v8 offset:4096
	ds_read_b128 v[102:105], v8 offset:8192
	ds_read_b128 v[106:109], v8 offset:12288
	ds_read_b128 v[110:113], v8 offset:16384
	ds_read_b128 v[114:117], v8 offset:20480
	ds_read_b128 v[118:121], v8 offset:24576
	ds_read_b128 v[122:125], v8 offset:28672
	ds_read_b128 v[126:129], v8
	ds_read_b128 v[134:137], v8 offset:32768
	v_add_u32_e32 v8, 16, v8
	s_waitcnt vmcnt(40) lgkmcnt(0)
	v_pk_fma_f32 v[196:197], v[154:155], v[126:127], v[196:197]
	v_pk_fma_f32 v[198:199], v[154:155], v[98:99], v[198:199]
	v_pk_fma_f32 v[200:201], v[154:155], v[102:103], v[200:201]
	v_pk_fma_f32 v[202:203], v[154:155], v[106:107], v[202:203]
	v_pk_fma_f32 v[204:205], v[154:155], v[110:111], v[204:205]
	v_pk_fma_f32 v[206:207], v[154:155], v[114:115], v[206:207]
	v_pk_fma_f32 v[208:209], v[154:155], v[118:119], v[208:209]
	v_pk_fma_f32 v[210:211], v[154:155], v[122:123], v[210:211]
	v_pk_fma_f32 v[212:213], v[154:155], v[134:135], v[212:213]
	v_pk_fma_f32 v[196:197], v[156:157], v[128:129], v[196:197]
	v_pk_fma_f32 v[198:199], v[156:157], v[100:101], v[198:199]
	v_pk_fma_f32 v[200:201], v[156:157], v[104:105], v[200:201]
	v_pk_fma_f32 v[202:203], v[156:157], v[108:109], v[202:203]
	v_pk_fma_f32 v[204:205], v[156:157], v[112:113], v[204:205]
	v_pk_fma_f32 v[206:207], v[156:157], v[116:117], v[206:207]
	v_pk_fma_f32 v[208:209], v[156:157], v[120:121], v[208:209]
	v_pk_fma_f32 v[210:211], v[156:157], v[124:125], v[210:211]
	v_pk_fma_f32 v[212:213], v[156:157], v[136:137], v[212:213]
	global_load_dword v154, v[194:195], off
	v_add_co_u32_e32 v194, vcc, 0x6000, v194
	v_addc_co_u32_e32 v195, vcc, 0, v195, vcc
	global_load_dword v155, v[194:195], off
	v_add_co_u32_e32 v194, vcc, 0x6000, v194
	v_addc_co_u32_e32 v195, vcc, 0, v195, vcc
	global_load_dword v156, v[194:195], off
	v_add_co_u32_e32 v194, vcc, 0x6000, v194
	v_addc_co_u32_e32 v195, vcc, 0, v195, vcc
	global_load_dword v157, v[194:195], off
	v_add_co_u32_e32 v194, vcc, 0x6000, v194
	v_addc_co_u32_e32 v195, vcc, 0, v195, vcc
	ds_read_b128 v[98:101], v8 offset:4096
	ds_read_b128 v[102:105], v8 offset:8192
	ds_read_b128 v[106:109], v8 offset:12288
	ds_read_b128 v[110:113], v8 offset:16384
	ds_read_b128 v[114:117], v8 offset:20480
	ds_read_b128 v[118:121], v8 offset:24576
	ds_read_b128 v[122:125], v8 offset:28672
	ds_read_b128 v[126:129], v8
	ds_read_b128 v[134:137], v8 offset:32768
	v_add_u32_e32 v8, 16, v8
	s_waitcnt vmcnt(40) lgkmcnt(0)
	v_pk_fma_f32 v[196:197], v[158:159], v[126:127], v[196:197]
	v_pk_fma_f32 v[198:199], v[158:159], v[98:99], v[198:199]
	v_pk_fma_f32 v[200:201], v[158:159], v[102:103], v[200:201]
	v_pk_fma_f32 v[202:203], v[158:159], v[106:107], v[202:203]
	v_pk_fma_f32 v[204:205], v[158:159], v[110:111], v[204:205]
	v_pk_fma_f32 v[206:207], v[158:159], v[114:115], v[206:207]
	v_pk_fma_f32 v[208:209], v[158:159], v[118:119], v[208:209]
	v_pk_fma_f32 v[210:211], v[158:159], v[122:123], v[210:211]
	v_pk_fma_f32 v[212:213], v[158:159], v[134:135], v[212:213]
	v_pk_fma_f32 v[196:197], v[160:161], v[128:129], v[196:197]
	v_pk_fma_f32 v[198:199], v[160:161], v[100:101], v[198:199]
	v_pk_fma_f32 v[200:201], v[160:161], v[104:105], v[200:201]
	v_pk_fma_f32 v[202:203], v[160:161], v[108:109], v[202:203]
	v_pk_fma_f32 v[204:205], v[160:161], v[112:113], v[204:205]
	v_pk_fma_f32 v[206:207], v[160:161], v[116:117], v[206:207]
	v_pk_fma_f32 v[208:209], v[160:161], v[120:121], v[208:209]
	v_pk_fma_f32 v[210:211], v[160:161], v[124:125], v[210:211]
	v_pk_fma_f32 v[212:213], v[160:161], v[136:137], v[212:213]
	global_load_dword v158, v[194:195], off
	v_add_co_u32_e32 v194, vcc, 0x6000, v194
	v_addc_co_u32_e32 v195, vcc, 0, v195, vcc
	global_load_dword v159, v[194:195], off
	v_add_co_u32_e32 v194, vcc, 0x6000, v194
	v_addc_co_u32_e32 v195, vcc, 0, v195, vcc
	global_load_dword v160, v[194:195], off
	v_add_co_u32_e32 v194, vcc, 0x6000, v194
	v_addc_co_u32_e32 v195, vcc, 0, v195, vcc
	global_load_dword v161, v[194:195], off
	v_add_co_u32_e32 v194, vcc, 0x6000, v194
	v_addc_co_u32_e32 v195, vcc, 0, v195, vcc
	ds_read_b128 v[98:101], v8 offset:4096
	ds_read_b128 v[102:105], v8 offset:8192
	ds_read_b128 v[106:109], v8 offset:12288
	ds_read_b128 v[110:113], v8 offset:16384
	ds_read_b128 v[114:117], v8 offset:20480
	ds_read_b128 v[118:121], v8 offset:24576
	ds_read_b128 v[122:125], v8 offset:28672
	ds_read_b128 v[126:129], v8
	ds_read_b128 v[134:137], v8 offset:32768
	v_add_u32_e32 v8, 16, v8
	s_waitcnt vmcnt(40) lgkmcnt(0)
	v_pk_fma_f32 v[196:197], v[162:163], v[126:127], v[196:197]
	v_pk_fma_f32 v[198:199], v[162:163], v[98:99], v[198:199]
	v_pk_fma_f32 v[200:201], v[162:163], v[102:103], v[200:201]
	v_pk_fma_f32 v[202:203], v[162:163], v[106:107], v[202:203]
	v_pk_fma_f32 v[204:205], v[162:163], v[110:111], v[204:205]
	v_pk_fma_f32 v[206:207], v[162:163], v[114:115], v[206:207]
	v_pk_fma_f32 v[208:209], v[162:163], v[118:119], v[208:209]
	v_pk_fma_f32 v[210:211], v[162:163], v[122:123], v[210:211]
	v_pk_fma_f32 v[212:213], v[162:163], v[134:135], v[212:213]
	v_pk_fma_f32 v[196:197], v[164:165], v[128:129], v[196:197]
	v_pk_fma_f32 v[198:199], v[164:165], v[100:101], v[198:199]
	v_pk_fma_f32 v[200:201], v[164:165], v[104:105], v[200:201]
	v_pk_fma_f32 v[202:203], v[164:165], v[108:109], v[202:203]
	v_pk_fma_f32 v[204:205], v[164:165], v[112:113], v[204:205]
	v_pk_fma_f32 v[206:207], v[164:165], v[116:117], v[206:207]
	v_pk_fma_f32 v[208:209], v[164:165], v[120:121], v[208:209]
	v_pk_fma_f32 v[210:211], v[164:165], v[124:125], v[210:211]
	v_pk_fma_f32 v[212:213], v[164:165], v[136:137], v[212:213]
	global_load_dword v162, v[194:195], off
	v_add_co_u32_e32 v194, vcc, 0x6000, v194
	v_addc_co_u32_e32 v195, vcc, 0, v195, vcc
	global_load_dword v163, v[194:195], off
	v_add_co_u32_e32 v194, vcc, 0x6000, v194
	v_addc_co_u32_e32 v195, vcc, 0, v195, vcc
	global_load_dword v164, v[194:195], off
	v_add_co_u32_e32 v194, vcc, 0x6000, v194
	v_addc_co_u32_e32 v195, vcc, 0, v195, vcc
	global_load_dword v165, v[194:195], off
	v_add_co_u32_e32 v194, vcc, 0x6000, v194
	v_addc_co_u32_e32 v195, vcc, 0, v195, vcc
	ds_read_b128 v[98:101], v8 offset:4096
	ds_read_b128 v[102:105], v8 offset:8192
	ds_read_b128 v[106:109], v8 offset:12288
	ds_read_b128 v[110:113], v8 offset:16384
	ds_read_b128 v[114:117], v8 offset:20480
	ds_read_b128 v[118:121], v8 offset:24576
	ds_read_b128 v[122:125], v8 offset:28672
	ds_read_b128 v[126:129], v8
	ds_read_b128 v[134:137], v8 offset:32768
	v_add_u32_e32 v8, 16, v8
	s_waitcnt vmcnt(40) lgkmcnt(0)
	v_pk_fma_f32 v[196:197], v[166:167], v[126:127], v[196:197]
	v_pk_fma_f32 v[198:199], v[166:167], v[98:99], v[198:199]
	v_pk_fma_f32 v[200:201], v[166:167], v[102:103], v[200:201]
	v_pk_fma_f32 v[202:203], v[166:167], v[106:107], v[202:203]
	v_pk_fma_f32 v[204:205], v[166:167], v[110:111], v[204:205]
	v_pk_fma_f32 v[206:207], v[166:167], v[114:115], v[206:207]
	v_pk_fma_f32 v[208:209], v[166:167], v[118:119], v[208:209]
	v_pk_fma_f32 v[210:211], v[166:167], v[122:123], v[210:211]
	v_pk_fma_f32 v[212:213], v[166:167], v[134:135], v[212:213]
	v_pk_fma_f32 v[196:197], v[168:169], v[128:129], v[196:197]
	v_pk_fma_f32 v[198:199], v[168:169], v[100:101], v[198:199]
	v_pk_fma_f32 v[200:201], v[168:169], v[104:105], v[200:201]
	v_pk_fma_f32 v[202:203], v[168:169], v[108:109], v[202:203]
	v_pk_fma_f32 v[204:205], v[168:169], v[112:113], v[204:205]
	v_pk_fma_f32 v[206:207], v[168:169], v[116:117], v[206:207]
	v_pk_fma_f32 v[208:209], v[168:169], v[120:121], v[208:209]
	v_pk_fma_f32 v[210:211], v[168:169], v[124:125], v[210:211]
	v_pk_fma_f32 v[212:213], v[168:169], v[136:137], v[212:213]
	global_load_dword v166, v[194:195], off
	v_add_co_u32_e32 v194, vcc, 0x6000, v194
	v_addc_co_u32_e32 v195, vcc, 0, v195, vcc
	global_load_dword v167, v[194:195], off
	v_add_co_u32_e32 v194, vcc, 0x6000, v194
	v_addc_co_u32_e32 v195, vcc, 0, v195, vcc
	global_load_dword v168, v[194:195], off
	v_add_co_u32_e32 v194, vcc, 0x6000, v194
	v_addc_co_u32_e32 v195, vcc, 0, v195, vcc
	global_load_dword v169, v[194:195], off
	v_add_co_u32_e32 v194, vcc, 0x6000, v194
	v_addc_co_u32_e32 v195, vcc, 0, v195, vcc
	ds_read_b128 v[98:101], v8 offset:4096
	ds_read_b128 v[102:105], v8 offset:8192
	ds_read_b128 v[106:109], v8 offset:12288
	ds_read_b128 v[110:113], v8 offset:16384
	ds_read_b128 v[114:117], v8 offset:20480
	ds_read_b128 v[118:121], v8 offset:24576
	ds_read_b128 v[122:125], v8 offset:28672
	ds_read_b128 v[126:129], v8
	ds_read_b128 v[134:137], v8 offset:32768
	v_add_u32_e32 v8, 16, v8
	s_waitcnt vmcnt(40) lgkmcnt(0)
	v_pk_fma_f32 v[196:197], v[170:171], v[126:127], v[196:197]
	v_pk_fma_f32 v[198:199], v[170:171], v[98:99], v[198:199]
	v_pk_fma_f32 v[200:201], v[170:171], v[102:103], v[200:201]
	v_pk_fma_f32 v[202:203], v[170:171], v[106:107], v[202:203]
	v_pk_fma_f32 v[204:205], v[170:171], v[110:111], v[204:205]
	v_pk_fma_f32 v[206:207], v[170:171], v[114:115], v[206:207]
	v_pk_fma_f32 v[208:209], v[170:171], v[118:119], v[208:209]
	v_pk_fma_f32 v[210:211], v[170:171], v[122:123], v[210:211]
	v_pk_fma_f32 v[212:213], v[170:171], v[134:135], v[212:213]
	v_pk_fma_f32 v[196:197], v[172:173], v[128:129], v[196:197]
	v_pk_fma_f32 v[198:199], v[172:173], v[100:101], v[198:199]
	v_pk_fma_f32 v[200:201], v[172:173], v[104:105], v[200:201]
	v_pk_fma_f32 v[202:203], v[172:173], v[108:109], v[202:203]
	v_pk_fma_f32 v[204:205], v[172:173], v[112:113], v[204:205]
	v_pk_fma_f32 v[206:207], v[172:173], v[116:117], v[206:207]
	v_pk_fma_f32 v[208:209], v[172:173], v[120:121], v[208:209]
	v_pk_fma_f32 v[210:211], v[172:173], v[124:125], v[210:211]
	v_pk_fma_f32 v[212:213], v[172:173], v[136:137], v[212:213]
	global_load_dword v170, v[194:195], off
	v_add_co_u32_e32 v194, vcc, 0x6000, v194
	v_addc_co_u32_e32 v195, vcc, 0, v195, vcc
	global_load_dword v171, v[194:195], off
	v_add_co_u32_e32 v194, vcc, 0x6000, v194
	v_addc_co_u32_e32 v195, vcc, 0, v195, vcc
	global_load_dword v172, v[194:195], off
	v_add_co_u32_e32 v194, vcc, 0x6000, v194
	v_addc_co_u32_e32 v195, vcc, 0, v195, vcc
	global_load_dword v173, v[194:195], off
	v_add_co_u32_e32 v194, vcc, 0x6000, v194
	v_addc_co_u32_e32 v195, vcc, 0, v195, vcc
	ds_read_b128 v[98:101], v8 offset:4096
	ds_read_b128 v[102:105], v8 offset:8192
	ds_read_b128 v[106:109], v8 offset:12288
	ds_read_b128 v[110:113], v8 offset:16384
	ds_read_b128 v[114:117], v8 offset:20480
	ds_read_b128 v[118:121], v8 offset:24576
	ds_read_b128 v[122:125], v8 offset:28672
	ds_read_b128 v[126:129], v8
	ds_read_b128 v[134:137], v8 offset:32768
	v_add_u32_e32 v8, 16, v8
	s_waitcnt vmcnt(40) lgkmcnt(0)
	v_pk_fma_f32 v[196:197], v[174:175], v[126:127], v[196:197]
	v_pk_fma_f32 v[198:199], v[174:175], v[98:99], v[198:199]
	v_pk_fma_f32 v[200:201], v[174:175], v[102:103], v[200:201]
	v_pk_fma_f32 v[202:203], v[174:175], v[106:107], v[202:203]
	v_pk_fma_f32 v[204:205], v[174:175], v[110:111], v[204:205]
	v_pk_fma_f32 v[206:207], v[174:175], v[114:115], v[206:207]
	v_pk_fma_f32 v[208:209], v[174:175], v[118:119], v[208:209]
	v_pk_fma_f32 v[210:211], v[174:175], v[122:123], v[210:211]
	v_pk_fma_f32 v[212:213], v[174:175], v[134:135], v[212:213]
	v_pk_fma_f32 v[196:197], v[176:177], v[128:129], v[196:197]
	v_pk_fma_f32 v[198:199], v[176:177], v[100:101], v[198:199]
	v_pk_fma_f32 v[200:201], v[176:177], v[104:105], v[200:201]
	v_pk_fma_f32 v[202:203], v[176:177], v[108:109], v[202:203]
	v_pk_fma_f32 v[204:205], v[176:177], v[112:113], v[204:205]
	v_pk_fma_f32 v[206:207], v[176:177], v[116:117], v[206:207]
	v_pk_fma_f32 v[208:209], v[176:177], v[120:121], v[208:209]
	v_pk_fma_f32 v[210:211], v[176:177], v[124:125], v[210:211]
	v_pk_fma_f32 v[212:213], v[176:177], v[136:137], v[212:213]
	global_load_dword v174, v[194:195], off
	v_add_co_u32_e32 v194, vcc, 0x6000, v194
	v_addc_co_u32_e32 v195, vcc, 0, v195, vcc
	global_load_dword v175, v[194:195], off
	v_add_co_u32_e32 v194, vcc, 0x6000, v194
	v_addc_co_u32_e32 v195, vcc, 0, v195, vcc
	global_load_dword v176, v[194:195], off
	v_add_co_u32_e32 v194, vcc, 0x6000, v194
	v_addc_co_u32_e32 v195, vcc, 0, v195, vcc
	global_load_dword v177, v[194:195], off
	v_add_co_u32_e32 v194, vcc, 0x6000, v194
	v_addc_co_u32_e32 v195, vcc, 0, v195, vcc
	ds_read_b128 v[98:101], v8 offset:4096
	ds_read_b128 v[102:105], v8 offset:8192
	ds_read_b128 v[106:109], v8 offset:12288
	ds_read_b128 v[110:113], v8 offset:16384
	ds_read_b128 v[114:117], v8 offset:20480
	ds_read_b128 v[118:121], v8 offset:24576
	ds_read_b128 v[122:125], v8 offset:28672
	ds_read_b128 v[126:129], v8
	ds_read_b128 v[134:137], v8 offset:32768
	v_add_u32_e32 v8, 16, v8
	s_waitcnt vmcnt(40) lgkmcnt(0)
	v_pk_fma_f32 v[196:197], v[178:179], v[126:127], v[196:197]
	v_pk_fma_f32 v[198:199], v[178:179], v[98:99], v[198:199]
	v_pk_fma_f32 v[200:201], v[178:179], v[102:103], v[200:201]
	v_pk_fma_f32 v[202:203], v[178:179], v[106:107], v[202:203]
	v_pk_fma_f32 v[204:205], v[178:179], v[110:111], v[204:205]
	v_pk_fma_f32 v[206:207], v[178:179], v[114:115], v[206:207]
	v_pk_fma_f32 v[208:209], v[178:179], v[118:119], v[208:209]
	v_pk_fma_f32 v[210:211], v[178:179], v[122:123], v[210:211]
	v_pk_fma_f32 v[212:213], v[178:179], v[134:135], v[212:213]
	v_pk_fma_f32 v[196:197], v[180:181], v[128:129], v[196:197]
	v_pk_fma_f32 v[198:199], v[180:181], v[100:101], v[198:199]
	v_pk_fma_f32 v[200:201], v[180:181], v[104:105], v[200:201]
	v_pk_fma_f32 v[202:203], v[180:181], v[108:109], v[202:203]
	v_pk_fma_f32 v[204:205], v[180:181], v[112:113], v[204:205]
	v_pk_fma_f32 v[206:207], v[180:181], v[116:117], v[206:207]
	v_pk_fma_f32 v[208:209], v[180:181], v[120:121], v[208:209]
	v_pk_fma_f32 v[210:211], v[180:181], v[124:125], v[210:211]
	v_pk_fma_f32 v[212:213], v[180:181], v[136:137], v[212:213]
	global_load_dword v178, v[194:195], off
	v_add_co_u32_e32 v194, vcc, 0x6000, v194
	v_addc_co_u32_e32 v195, vcc, 0, v195, vcc
	global_load_dword v179, v[194:195], off
	v_add_co_u32_e32 v194, vcc, 0x6000, v194
	v_addc_co_u32_e32 v195, vcc, 0, v195, vcc
	global_load_dword v180, v[194:195], off
	v_add_co_u32_e32 v194, vcc, 0x6000, v194
	v_addc_co_u32_e32 v195, vcc, 0, v195, vcc
	global_load_dword v181, v[194:195], off
	v_add_co_u32_e32 v194, vcc, 0x6000, v194
	v_addc_co_u32_e32 v195, vcc, 0, v195, vcc
	ds_read_b128 v[98:101], v8 offset:4096
	ds_read_b128 v[102:105], v8 offset:8192
	ds_read_b128 v[106:109], v8 offset:12288
	ds_read_b128 v[110:113], v8 offset:16384
	ds_read_b128 v[114:117], v8 offset:20480
	ds_read_b128 v[118:121], v8 offset:24576
	ds_read_b128 v[122:125], v8 offset:28672
	ds_read_b128 v[126:129], v8
	ds_read_b128 v[134:137], v8 offset:32768
	v_add_u32_e32 v8, 16, v8
	s_waitcnt vmcnt(40) lgkmcnt(0)
	v_pk_fma_f32 v[196:197], v[182:183], v[126:127], v[196:197]
	v_pk_fma_f32 v[198:199], v[182:183], v[98:99], v[198:199]
	v_pk_fma_f32 v[200:201], v[182:183], v[102:103], v[200:201]
	v_pk_fma_f32 v[202:203], v[182:183], v[106:107], v[202:203]
	v_pk_fma_f32 v[204:205], v[182:183], v[110:111], v[204:205]
	v_pk_fma_f32 v[206:207], v[182:183], v[114:115], v[206:207]
	v_pk_fma_f32 v[208:209], v[182:183], v[118:119], v[208:209]
	v_pk_fma_f32 v[210:211], v[182:183], v[122:123], v[210:211]
	v_pk_fma_f32 v[212:213], v[182:183], v[134:135], v[212:213]
	v_pk_fma_f32 v[196:197], v[184:185], v[128:129], v[196:197]
	v_pk_fma_f32 v[198:199], v[184:185], v[100:101], v[198:199]
	v_pk_fma_f32 v[200:201], v[184:185], v[104:105], v[200:201]
	v_pk_fma_f32 v[202:203], v[184:185], v[108:109], v[202:203]
	v_pk_fma_f32 v[204:205], v[184:185], v[112:113], v[204:205]
	v_pk_fma_f32 v[206:207], v[184:185], v[116:117], v[206:207]
	v_pk_fma_f32 v[208:209], v[184:185], v[120:121], v[208:209]
	v_pk_fma_f32 v[210:211], v[184:185], v[124:125], v[210:211]
	v_pk_fma_f32 v[212:213], v[184:185], v[136:137], v[212:213]
	global_load_dword v182, v[194:195], off
	v_add_co_u32_e32 v194, vcc, 0x6000, v194
	v_addc_co_u32_e32 v195, vcc, 0, v195, vcc
	global_load_dword v183, v[194:195], off
	v_add_co_u32_e32 v194, vcc, 0x6000, v194
	v_addc_co_u32_e32 v195, vcc, 0, v195, vcc
	global_load_dword v184, v[194:195], off
	v_add_co_u32_e32 v194, vcc, 0x6000, v194
	v_addc_co_u32_e32 v195, vcc, 0, v195, vcc
	global_load_dword v185, v[194:195], off
	v_add_co_u32_e32 v194, vcc, 0x6000, v194
	v_addc_co_u32_e32 v195, vcc, 0, v195, vcc
	ds_read_b128 v[98:101], v8 offset:4096
	ds_read_b128 v[102:105], v8 offset:8192
	ds_read_b128 v[106:109], v8 offset:12288
	ds_read_b128 v[110:113], v8 offset:16384
	ds_read_b128 v[114:117], v8 offset:20480
	ds_read_b128 v[118:121], v8 offset:24576
	ds_read_b128 v[122:125], v8 offset:28672
	ds_read_b128 v[126:129], v8
	ds_read_b128 v[134:137], v8 offset:32768
	v_add_u32_e32 v8, 16, v8
	s_waitcnt vmcnt(40) lgkmcnt(0)
	v_pk_fma_f32 v[196:197], v[186:187], v[126:127], v[196:197]
	v_pk_fma_f32 v[198:199], v[186:187], v[98:99], v[198:199]
	v_pk_fma_f32 v[200:201], v[186:187], v[102:103], v[200:201]
	v_pk_fma_f32 v[202:203], v[186:187], v[106:107], v[202:203]
	v_pk_fma_f32 v[204:205], v[186:187], v[110:111], v[204:205]
	v_pk_fma_f32 v[206:207], v[186:187], v[114:115], v[206:207]
	v_pk_fma_f32 v[208:209], v[186:187], v[118:119], v[208:209]
	v_pk_fma_f32 v[210:211], v[186:187], v[122:123], v[210:211]
	v_pk_fma_f32 v[212:213], v[186:187], v[134:135], v[212:213]
	v_pk_fma_f32 v[196:197], v[188:189], v[128:129], v[196:197]
	v_pk_fma_f32 v[198:199], v[188:189], v[100:101], v[198:199]
	v_pk_fma_f32 v[200:201], v[188:189], v[104:105], v[200:201]
	v_pk_fma_f32 v[202:203], v[188:189], v[108:109], v[202:203]
	v_pk_fma_f32 v[204:205], v[188:189], v[112:113], v[204:205]
	v_pk_fma_f32 v[206:207], v[188:189], v[116:117], v[206:207]
	v_pk_fma_f32 v[208:209], v[188:189], v[120:121], v[208:209]
	v_pk_fma_f32 v[210:211], v[188:189], v[124:125], v[210:211]
	v_pk_fma_f32 v[212:213], v[188:189], v[136:137], v[212:213]
	global_load_dword v186, v[194:195], off
	v_add_co_u32_e32 v194, vcc, 0x6000, v194
	v_addc_co_u32_e32 v195, vcc, 0, v195, vcc
	global_load_dword v187, v[194:195], off
	v_add_co_u32_e32 v194, vcc, 0x6000, v194
	v_addc_co_u32_e32 v195, vcc, 0, v195, vcc
	global_load_dword v188, v[194:195], off
	v_add_co_u32_e32 v194, vcc, 0x6000, v194
	v_addc_co_u32_e32 v195, vcc, 0, v195, vcc
	global_load_dword v189, v[194:195], off
	ds_read_b128 v[98:101], v8 offset:4096
	ds_read_b128 v[102:105], v8 offset:8192
	ds_read_b128 v[106:109], v8 offset:12288
	ds_read_b128 v[110:113], v8 offset:16384
	ds_read_b128 v[114:117], v8 offset:20480
	ds_read_b128 v[118:121], v8 offset:24576
	ds_read_b128 v[122:125], v8 offset:28672
	ds_read_b128 v[126:129], v8
	ds_read_b128 v[134:137], v8 offset:32768
	v_add_u32_e32 v8, 16, v8
	s_waitcnt vmcnt(40) lgkmcnt(0)
	v_pk_fma_f32 v[196:197], v[190:191], v[126:127], v[196:197]
	v_pk_fma_f32 v[198:199], v[190:191], v[98:99], v[198:199]
	v_pk_fma_f32 v[200:201], v[190:191], v[102:103], v[200:201]
	v_pk_fma_f32 v[202:203], v[190:191], v[106:107], v[202:203]
	v_pk_fma_f32 v[204:205], v[190:191], v[110:111], v[204:205]
	v_pk_fma_f32 v[206:207], v[190:191], v[114:115], v[206:207]
	v_pk_fma_f32 v[208:209], v[190:191], v[118:119], v[208:209]
	v_pk_fma_f32 v[210:211], v[190:191], v[122:123], v[210:211]
	v_pk_fma_f32 v[212:213], v[190:191], v[134:135], v[212:213]
	v_pk_fma_f32 v[196:197], v[192:193], v[128:129], v[196:197]
	v_pk_fma_f32 v[198:199], v[192:193], v[100:101], v[198:199]
	v_pk_fma_f32 v[200:201], v[192:193], v[104:105], v[200:201]
	v_pk_fma_f32 v[202:203], v[192:193], v[108:109], v[202:203]
	v_pk_fma_f32 v[204:205], v[192:193], v[112:113], v[204:205]
	v_pk_fma_f32 v[206:207], v[192:193], v[116:117], v[206:207]
	v_pk_fma_f32 v[208:209], v[192:193], v[120:121], v[208:209]
	v_pk_fma_f32 v[210:211], v[192:193], v[124:125], v[210:211]
	v_pk_fma_f32 v[212:213], v[192:193], v[136:137], v[212:213]
	ds_read_b128 v[98:101], v8 offset:4096
	ds_read_b128 v[102:105], v8 offset:8192
	ds_read_b128 v[106:109], v8 offset:12288
	ds_read_b128 v[110:113], v8 offset:16384
	ds_read_b128 v[114:117], v8 offset:20480
	ds_read_b128 v[118:121], v8 offset:24576
	ds_read_b128 v[122:125], v8 offset:28672
	ds_read_b128 v[126:129], v8
	ds_read_b128 v[134:137], v8 offset:32768
	v_add_u32_e32 v8, 16, v8
	s_waitcnt vmcnt(36) lgkmcnt(0)
	v_pk_fma_f32 v[196:197], v[150:151], v[126:127], v[196:197]
	v_pk_fma_f32 v[198:199], v[150:151], v[98:99], v[198:199]
	v_pk_fma_f32 v[200:201], v[150:151], v[102:103], v[200:201]
	v_pk_fma_f32 v[202:203], v[150:151], v[106:107], v[202:203]
	v_pk_fma_f32 v[204:205], v[150:151], v[110:111], v[204:205]
	v_pk_fma_f32 v[206:207], v[150:151], v[114:115], v[206:207]
	v_pk_fma_f32 v[208:209], v[150:151], v[118:119], v[208:209]
	v_pk_fma_f32 v[210:211], v[150:151], v[122:123], v[210:211]
	v_pk_fma_f32 v[212:213], v[150:151], v[134:135], v[212:213]
	v_pk_fma_f32 v[196:197], v[152:153], v[128:129], v[196:197]
	v_pk_fma_f32 v[198:199], v[152:153], v[100:101], v[198:199]
	v_pk_fma_f32 v[200:201], v[152:153], v[104:105], v[200:201]
	v_pk_fma_f32 v[202:203], v[152:153], v[108:109], v[202:203]
	v_pk_fma_f32 v[204:205], v[152:153], v[112:113], v[204:205]
	v_pk_fma_f32 v[206:207], v[152:153], v[116:117], v[206:207]
	v_pk_fma_f32 v[208:209], v[152:153], v[120:121], v[208:209]
	v_pk_fma_f32 v[210:211], v[152:153], v[124:125], v[210:211]
	v_pk_fma_f32 v[212:213], v[152:153], v[136:137], v[212:213]
	ds_read_b128 v[98:101], v8 offset:4096
	ds_read_b128 v[102:105], v8 offset:8192
	ds_read_b128 v[106:109], v8 offset:12288
	ds_read_b128 v[110:113], v8 offset:16384
	ds_read_b128 v[114:117], v8 offset:20480
	ds_read_b128 v[118:121], v8 offset:24576
	ds_read_b128 v[122:125], v8 offset:28672
	ds_read_b128 v[126:129], v8
	ds_read_b128 v[134:137], v8 offset:32768
	v_add_u32_e32 v8, 16, v8
	s_waitcnt vmcnt(32) lgkmcnt(0)
	v_pk_fma_f32 v[196:197], v[154:155], v[126:127], v[196:197]
	v_pk_fma_f32 v[198:199], v[154:155], v[98:99], v[198:199]
	v_pk_fma_f32 v[200:201], v[154:155], v[102:103], v[200:201]
	v_pk_fma_f32 v[202:203], v[154:155], v[106:107], v[202:203]
	v_pk_fma_f32 v[204:205], v[154:155], v[110:111], v[204:205]
	v_pk_fma_f32 v[206:207], v[154:155], v[114:115], v[206:207]
	v_pk_fma_f32 v[208:209], v[154:155], v[118:119], v[208:209]
	v_pk_fma_f32 v[210:211], v[154:155], v[122:123], v[210:211]
	v_pk_fma_f32 v[212:213], v[154:155], v[134:135], v[212:213]
	v_pk_fma_f32 v[196:197], v[156:157], v[128:129], v[196:197]
	v_pk_fma_f32 v[198:199], v[156:157], v[100:101], v[198:199]
	v_pk_fma_f32 v[200:201], v[156:157], v[104:105], v[200:201]
	v_pk_fma_f32 v[202:203], v[156:157], v[108:109], v[202:203]
	v_pk_fma_f32 v[204:205], v[156:157], v[112:113], v[204:205]
	v_pk_fma_f32 v[206:207], v[156:157], v[116:117], v[206:207]
	v_pk_fma_f32 v[208:209], v[156:157], v[120:121], v[208:209]
	v_pk_fma_f32 v[210:211], v[156:157], v[124:125], v[210:211]
	v_pk_fma_f32 v[212:213], v[156:157], v[136:137], v[212:213]
	ds_read_b128 v[98:101], v8 offset:4096
	ds_read_b128 v[102:105], v8 offset:8192
	ds_read_b128 v[106:109], v8 offset:12288
	ds_read_b128 v[110:113], v8 offset:16384
	ds_read_b128 v[114:117], v8 offset:20480
	ds_read_b128 v[118:121], v8 offset:24576
	ds_read_b128 v[122:125], v8 offset:28672
	ds_read_b128 v[126:129], v8
	ds_read_b128 v[134:137], v8 offset:32768
	v_add_u32_e32 v8, 16, v8
	s_waitcnt vmcnt(28) lgkmcnt(0)
	v_pk_fma_f32 v[196:197], v[158:159], v[126:127], v[196:197]
	v_pk_fma_f32 v[198:199], v[158:159], v[98:99], v[198:199]
	v_pk_fma_f32 v[200:201], v[158:159], v[102:103], v[200:201]
	v_pk_fma_f32 v[202:203], v[158:159], v[106:107], v[202:203]
	v_pk_fma_f32 v[204:205], v[158:159], v[110:111], v[204:205]
	v_pk_fma_f32 v[206:207], v[158:159], v[114:115], v[206:207]
	v_pk_fma_f32 v[208:209], v[158:159], v[118:119], v[208:209]
	v_pk_fma_f32 v[210:211], v[158:159], v[122:123], v[210:211]
	v_pk_fma_f32 v[212:213], v[158:159], v[134:135], v[212:213]
	v_pk_fma_f32 v[196:197], v[160:161], v[128:129], v[196:197]
	v_pk_fma_f32 v[198:199], v[160:161], v[100:101], v[198:199]
	v_pk_fma_f32 v[200:201], v[160:161], v[104:105], v[200:201]
	v_pk_fma_f32 v[202:203], v[160:161], v[108:109], v[202:203]
	v_pk_fma_f32 v[204:205], v[160:161], v[112:113], v[204:205]
	v_pk_fma_f32 v[206:207], v[160:161], v[116:117], v[206:207]
	v_pk_fma_f32 v[208:209], v[160:161], v[120:121], v[208:209]
	v_pk_fma_f32 v[210:211], v[160:161], v[124:125], v[210:211]
	v_pk_fma_f32 v[212:213], v[160:161], v[136:137], v[212:213]
	ds_read_b128 v[98:101], v8 offset:4096
	ds_read_b128 v[102:105], v8 offset:8192
	ds_read_b128 v[106:109], v8 offset:12288
	ds_read_b128 v[110:113], v8 offset:16384
	ds_read_b128 v[114:117], v8 offset:20480
	ds_read_b128 v[118:121], v8 offset:24576
	ds_read_b128 v[122:125], v8 offset:28672
	ds_read_b128 v[126:129], v8
	ds_read_b128 v[134:137], v8 offset:32768
	v_add_u32_e32 v8, 16, v8
	s_waitcnt vmcnt(24) lgkmcnt(0)
	v_pk_fma_f32 v[196:197], v[162:163], v[126:127], v[196:197]
	v_pk_fma_f32 v[198:199], v[162:163], v[98:99], v[198:199]
	v_pk_fma_f32 v[200:201], v[162:163], v[102:103], v[200:201]
	v_pk_fma_f32 v[202:203], v[162:163], v[106:107], v[202:203]
	v_pk_fma_f32 v[204:205], v[162:163], v[110:111], v[204:205]
	v_pk_fma_f32 v[206:207], v[162:163], v[114:115], v[206:207]
	v_pk_fma_f32 v[208:209], v[162:163], v[118:119], v[208:209]
	v_pk_fma_f32 v[210:211], v[162:163], v[122:123], v[210:211]
	v_pk_fma_f32 v[212:213], v[162:163], v[134:135], v[212:213]
	v_pk_fma_f32 v[196:197], v[164:165], v[128:129], v[196:197]
	v_pk_fma_f32 v[198:199], v[164:165], v[100:101], v[198:199]
	v_pk_fma_f32 v[200:201], v[164:165], v[104:105], v[200:201]
	v_pk_fma_f32 v[202:203], v[164:165], v[108:109], v[202:203]
	v_pk_fma_f32 v[204:205], v[164:165], v[112:113], v[204:205]
	v_pk_fma_f32 v[206:207], v[164:165], v[116:117], v[206:207]
	v_pk_fma_f32 v[208:209], v[164:165], v[120:121], v[208:209]
	v_pk_fma_f32 v[210:211], v[164:165], v[124:125], v[210:211]
	v_pk_fma_f32 v[212:213], v[164:165], v[136:137], v[212:213]
	ds_read_b128 v[98:101], v8 offset:4096
	ds_read_b128 v[102:105], v8 offset:8192
	ds_read_b128 v[106:109], v8 offset:12288
	ds_read_b128 v[110:113], v8 offset:16384
	ds_read_b128 v[114:117], v8 offset:20480
	ds_read_b128 v[118:121], v8 offset:24576
	ds_read_b128 v[122:125], v8 offset:28672
	ds_read_b128 v[126:129], v8
	ds_read_b128 v[134:137], v8 offset:32768
	v_add_u32_e32 v8, 16, v8
	s_waitcnt vmcnt(20) lgkmcnt(0)
	v_pk_fma_f32 v[196:197], v[166:167], v[126:127], v[196:197]
	v_pk_fma_f32 v[198:199], v[166:167], v[98:99], v[198:199]
	v_pk_fma_f32 v[200:201], v[166:167], v[102:103], v[200:201]
	v_pk_fma_f32 v[202:203], v[166:167], v[106:107], v[202:203]
	v_pk_fma_f32 v[204:205], v[166:167], v[110:111], v[204:205]
	v_pk_fma_f32 v[206:207], v[166:167], v[114:115], v[206:207]
	v_pk_fma_f32 v[208:209], v[166:167], v[118:119], v[208:209]
	v_pk_fma_f32 v[210:211], v[166:167], v[122:123], v[210:211]
	v_pk_fma_f32 v[212:213], v[166:167], v[134:135], v[212:213]
	v_pk_fma_f32 v[196:197], v[168:169], v[128:129], v[196:197]
	v_pk_fma_f32 v[198:199], v[168:169], v[100:101], v[198:199]
	v_pk_fma_f32 v[200:201], v[168:169], v[104:105], v[200:201]
	v_pk_fma_f32 v[202:203], v[168:169], v[108:109], v[202:203]
	v_pk_fma_f32 v[204:205], v[168:169], v[112:113], v[204:205]
	v_pk_fma_f32 v[206:207], v[168:169], v[116:117], v[206:207]
	v_pk_fma_f32 v[208:209], v[168:169], v[120:121], v[208:209]
	v_pk_fma_f32 v[210:211], v[168:169], v[124:125], v[210:211]
	v_pk_fma_f32 v[212:213], v[168:169], v[136:137], v[212:213]
	ds_read_b128 v[98:101], v8 offset:4096
	ds_read_b128 v[102:105], v8 offset:8192
	ds_read_b128 v[106:109], v8 offset:12288
	ds_read_b128 v[110:113], v8 offset:16384
	ds_read_b128 v[114:117], v8 offset:20480
	ds_read_b128 v[118:121], v8 offset:24576
	ds_read_b128 v[122:125], v8 offset:28672
	ds_read_b128 v[126:129], v8
	ds_read_b128 v[134:137], v8 offset:32768
	v_add_u32_e32 v8, 16, v8
	s_waitcnt vmcnt(16) lgkmcnt(0)
	v_pk_fma_f32 v[196:197], v[170:171], v[126:127], v[196:197]
	v_pk_fma_f32 v[198:199], v[170:171], v[98:99], v[198:199]
	v_pk_fma_f32 v[200:201], v[170:171], v[102:103], v[200:201]
	v_pk_fma_f32 v[202:203], v[170:171], v[106:107], v[202:203]
	v_pk_fma_f32 v[204:205], v[170:171], v[110:111], v[204:205]
	v_pk_fma_f32 v[206:207], v[170:171], v[114:115], v[206:207]
	v_pk_fma_f32 v[208:209], v[170:171], v[118:119], v[208:209]
	v_pk_fma_f32 v[210:211], v[170:171], v[122:123], v[210:211]
	v_pk_fma_f32 v[212:213], v[170:171], v[134:135], v[212:213]
	v_pk_fma_f32 v[196:197], v[172:173], v[128:129], v[196:197]
	v_pk_fma_f32 v[198:199], v[172:173], v[100:101], v[198:199]
	v_pk_fma_f32 v[200:201], v[172:173], v[104:105], v[200:201]
	v_pk_fma_f32 v[202:203], v[172:173], v[108:109], v[202:203]
	v_pk_fma_f32 v[204:205], v[172:173], v[112:113], v[204:205]
	v_pk_fma_f32 v[206:207], v[172:173], v[116:117], v[206:207]
	v_pk_fma_f32 v[208:209], v[172:173], v[120:121], v[208:209]
	v_pk_fma_f32 v[210:211], v[172:173], v[124:125], v[210:211]
	v_pk_fma_f32 v[212:213], v[172:173], v[136:137], v[212:213]
	ds_read_b128 v[98:101], v8 offset:4096
	ds_read_b128 v[102:105], v8 offset:8192
	ds_read_b128 v[106:109], v8 offset:12288
	ds_read_b128 v[110:113], v8 offset:16384
	ds_read_b128 v[114:117], v8 offset:20480
	ds_read_b128 v[118:121], v8 offset:24576
	ds_read_b128 v[122:125], v8 offset:28672
	ds_read_b128 v[126:129], v8
	ds_read_b128 v[134:137], v8 offset:32768
	v_add_u32_e32 v8, 16, v8
	s_waitcnt vmcnt(12) lgkmcnt(0)
	v_pk_fma_f32 v[196:197], v[174:175], v[126:127], v[196:197]
	v_pk_fma_f32 v[198:199], v[174:175], v[98:99], v[198:199]
	v_pk_fma_f32 v[200:201], v[174:175], v[102:103], v[200:201]
	v_pk_fma_f32 v[202:203], v[174:175], v[106:107], v[202:203]
	v_pk_fma_f32 v[204:205], v[174:175], v[110:111], v[204:205]
	v_pk_fma_f32 v[206:207], v[174:175], v[114:115], v[206:207]
	v_pk_fma_f32 v[208:209], v[174:175], v[118:119], v[208:209]
	v_pk_fma_f32 v[210:211], v[174:175], v[122:123], v[210:211]
	v_pk_fma_f32 v[212:213], v[174:175], v[134:135], v[212:213]
	v_pk_fma_f32 v[196:197], v[176:177], v[128:129], v[196:197]
	v_pk_fma_f32 v[198:199], v[176:177], v[100:101], v[198:199]
	v_pk_fma_f32 v[200:201], v[176:177], v[104:105], v[200:201]
	v_pk_fma_f32 v[202:203], v[176:177], v[108:109], v[202:203]
	v_pk_fma_f32 v[204:205], v[176:177], v[112:113], v[204:205]
	v_pk_fma_f32 v[206:207], v[176:177], v[116:117], v[206:207]
	v_pk_fma_f32 v[208:209], v[176:177], v[120:121], v[208:209]
	v_pk_fma_f32 v[210:211], v[176:177], v[124:125], v[210:211]
	v_pk_fma_f32 v[212:213], v[176:177], v[136:137], v[212:213]
	ds_read_b128 v[98:101], v8 offset:4096
	ds_read_b128 v[102:105], v8 offset:8192
	ds_read_b128 v[106:109], v8 offset:12288
	ds_read_b128 v[110:113], v8 offset:16384
	ds_read_b128 v[114:117], v8 offset:20480
	ds_read_b128 v[118:121], v8 offset:24576
	ds_read_b128 v[122:125], v8 offset:28672
	ds_read_b128 v[126:129], v8
	ds_read_b128 v[134:137], v8 offset:32768
	v_add_u32_e32 v8, 16, v8
	s_waitcnt vmcnt(8) lgkmcnt(0)
	v_pk_fma_f32 v[196:197], v[178:179], v[126:127], v[196:197]
	v_pk_fma_f32 v[198:199], v[178:179], v[98:99], v[198:199]
	v_pk_fma_f32 v[200:201], v[178:179], v[102:103], v[200:201]
	v_pk_fma_f32 v[202:203], v[178:179], v[106:107], v[202:203]
	v_pk_fma_f32 v[204:205], v[178:179], v[110:111], v[204:205]
	v_pk_fma_f32 v[206:207], v[178:179], v[114:115], v[206:207]
	v_pk_fma_f32 v[208:209], v[178:179], v[118:119], v[208:209]
	v_pk_fma_f32 v[210:211], v[178:179], v[122:123], v[210:211]
	v_pk_fma_f32 v[212:213], v[178:179], v[134:135], v[212:213]
	v_pk_fma_f32 v[196:197], v[180:181], v[128:129], v[196:197]
	v_pk_fma_f32 v[198:199], v[180:181], v[100:101], v[198:199]
	v_pk_fma_f32 v[200:201], v[180:181], v[104:105], v[200:201]
	v_pk_fma_f32 v[202:203], v[180:181], v[108:109], v[202:203]
	v_pk_fma_f32 v[204:205], v[180:181], v[112:113], v[204:205]
	v_pk_fma_f32 v[206:207], v[180:181], v[116:117], v[206:207]
	v_pk_fma_f32 v[208:209], v[180:181], v[120:121], v[208:209]
	v_pk_fma_f32 v[210:211], v[180:181], v[124:125], v[210:211]
	v_pk_fma_f32 v[212:213], v[180:181], v[136:137], v[212:213]
	ds_read_b128 v[98:101], v8 offset:4096
	ds_read_b128 v[102:105], v8 offset:8192
	ds_read_b128 v[106:109], v8 offset:12288
	ds_read_b128 v[110:113], v8 offset:16384
	ds_read_b128 v[114:117], v8 offset:20480
	ds_read_b128 v[118:121], v8 offset:24576
	ds_read_b128 v[122:125], v8 offset:28672
	ds_read_b128 v[126:129], v8
	ds_read_b128 v[134:137], v8 offset:32768
	v_add_u32_e32 v8, 16, v8
	s_waitcnt vmcnt(4) lgkmcnt(0)
	v_pk_fma_f32 v[196:197], v[182:183], v[126:127], v[196:197]
	v_pk_fma_f32 v[198:199], v[182:183], v[98:99], v[198:199]
	v_pk_fma_f32 v[200:201], v[182:183], v[102:103], v[200:201]
	v_pk_fma_f32 v[202:203], v[182:183], v[106:107], v[202:203]
	v_pk_fma_f32 v[204:205], v[182:183], v[110:111], v[204:205]
	v_pk_fma_f32 v[206:207], v[182:183], v[114:115], v[206:207]
	v_pk_fma_f32 v[208:209], v[182:183], v[118:119], v[208:209]
	v_pk_fma_f32 v[210:211], v[182:183], v[122:123], v[210:211]
	v_pk_fma_f32 v[212:213], v[182:183], v[134:135], v[212:213]
	v_pk_fma_f32 v[196:197], v[184:185], v[128:129], v[196:197]
	v_pk_fma_f32 v[198:199], v[184:185], v[100:101], v[198:199]
	v_pk_fma_f32 v[200:201], v[184:185], v[104:105], v[200:201]
	v_pk_fma_f32 v[202:203], v[184:185], v[108:109], v[202:203]
	v_pk_fma_f32 v[204:205], v[184:185], v[112:113], v[204:205]
	v_pk_fma_f32 v[206:207], v[184:185], v[116:117], v[206:207]
	v_pk_fma_f32 v[208:209], v[184:185], v[120:121], v[208:209]
	v_pk_fma_f32 v[210:211], v[184:185], v[124:125], v[210:211]
	v_pk_fma_f32 v[212:213], v[184:185], v[136:137], v[212:213]
	ds_read_b128 v[98:101], v8 offset:4096
	ds_read_b128 v[102:105], v8 offset:8192
	ds_read_b128 v[106:109], v8 offset:12288
	ds_read_b128 v[110:113], v8 offset:16384
	ds_read_b128 v[114:117], v8 offset:20480
	ds_read_b128 v[118:121], v8 offset:24576
	ds_read_b128 v[122:125], v8 offset:28672
	ds_read_b128 v[126:129], v8
	ds_read_b128 v[134:137], v8 offset:32768
	v_add_u32_e32 v8, 16, v8
	s_waitcnt vmcnt(0) lgkmcnt(0)
	v_pk_fma_f32 v[196:197], v[186:187], v[126:127], v[196:197]
	v_pk_fma_f32 v[198:199], v[186:187], v[98:99], v[198:199]
	v_pk_fma_f32 v[200:201], v[186:187], v[102:103], v[200:201]
	v_pk_fma_f32 v[202:203], v[186:187], v[106:107], v[202:203]
	v_pk_fma_f32 v[204:205], v[186:187], v[110:111], v[204:205]
	v_pk_fma_f32 v[206:207], v[186:187], v[114:115], v[206:207]
	v_pk_fma_f32 v[208:209], v[186:187], v[118:119], v[208:209]
	v_pk_fma_f32 v[210:211], v[186:187], v[122:123], v[210:211]
	v_pk_fma_f32 v[212:213], v[186:187], v[134:135], v[212:213]
	v_pk_fma_f32 v[196:197], v[188:189], v[128:129], v[196:197]
	v_pk_fma_f32 v[198:199], v[188:189], v[100:101], v[198:199]
	v_pk_fma_f32 v[200:201], v[188:189], v[104:105], v[200:201]
	v_pk_fma_f32 v[202:203], v[188:189], v[108:109], v[202:203]
	v_pk_fma_f32 v[204:205], v[188:189], v[112:113], v[204:205]
	v_pk_fma_f32 v[206:207], v[188:189], v[116:117], v[206:207]
	v_pk_fma_f32 v[208:209], v[188:189], v[120:121], v[208:209]
	v_pk_fma_f32 v[210:211], v[188:189], v[124:125], v[210:211]
	v_pk_fma_f32 v[212:213], v[188:189], v[136:137], v[212:213]
	v_add_f32_e32 v4, v196, v197
	v_add_f32_e32 v5, v198, v199
	v_add_f32_e32 v68, v200, v201
	v_add_f32_e32 v69, v202, v203
	v_add_f32_e32 v70, v204, v205
	v_add_f32_e32 v71, v206, v207
	v_add_f32_e32 v72, v208, v209
	v_add_f32_e32 v73, v210, v211
	v_add_f32_e32 v23, v212, v213
	v_add_u32_e32 v2, 0x9000, v76
	ds_write2_b32 v2, v4, v5 offset1:32
	ds_write2_b32 v2, v68, v69 offset0:64 offset1:96
	ds_write2_b32 v2, v70, v71 offset0:128 offset1:160
	ds_write2_b32 v2, v72, v73 offset0:192 offset1:224
	ds_write_b32 v76, v23 offset:37888
	v_mov_b32_e32 v2, s63
	v_mov_b32_e32 v4, s75
	s_waitcnt lgkmcnt(0)
	s_barrier
	ds_read_b64 v[2:3], v2
	ds_read_b64 v[4:5], v4
	v_lshl_or_b32 v8, v1, 5, v74
	v_add_u32_e32 v8, 0xfffdd800, v8
	s_mov_b64 s[52:53], 0
	s_waitcnt lgkmcnt(1)
	v_lshl_add_u64 v[2:3], v[2:3], 0, s[36:37]
	s_waitcnt lgkmcnt(0)
	v_lshl_add_u64 v[4:5], v[8:9], 2, v[4:5]
	v_mov_b32_e32 v8, v84
	v_mov_b32_e32 v23, v83
	v_mov_b32_e32 v61, v82
	v_mov_b32_e32 v65, v89
